# SSD counted vmcnt + loads hoisted, G/M role remap; P5 epilogue store pairs merged to dwordx4
# speedup vs baseline: 1.0347x; 1.0144x over previous
; __device__ __forceinline__ void ssd_item(const Params& P, LAS unsigned char* lds, int item, int tid, int wave, int lane) {
;     const int b = item >> 4, h = item & 15, g = h >> 3;
;     const bf16_t* PROJ = (const bf16_t*)(P.ws + WS_PROJ); bf16_t* YS = (bf16_t*)(P.ws + WS_YSSD);
;     const float dtb = P.dt_bias[h];
;     const float Ah = -__expf(P.a_log[h]), Dh = P.d_skip[h];
;     const int r = lane & 31, hh = lane >> 5;
;     const int xrow0 = tid >> 3, xoct = tid & 7;
;     const int brow0 = tid >> 5, bsel = (tid >> 4) & 1, boct = tid & 15;
;     const int yb = wave & 3, pb = wave >> 2;
;     const int ycol = h * 64 + pb * 32 + r;
;     const __amdgpu_buffer_rsrc_t prs = __builtin_amdgcn_make_buffer_rsrc((void*)PROJ, 0, 0x7fffffff, 0x00020000);
;     const __amdgpu_buffer_rsrc_t yrs = __builtin_amdgcn_make_buffer_rsrc((void*)YS, 0, 0x7fffffff, 0x00020000);
;     const int yc = lane & 15, yg = lane >> 4;
;     const unsigned zvoff = (unsigned)(4 * yg * LDP + OFF_Z + h * 64 + 4 * yc) * 2u, xvoff = (unsigned)(4 * yg * LDP + OFF_XBC + h * 64 + 4 * yc) * 2u, yvoff = (unsigned)(4 * yg * 1024 + h * 64 + 4 * yc) * 2u;
;     ...
;         const int lb = wave >> 1, sb0 = 2 * (wave & 1);
;         f32x16 g0, g1; for (int i = 0; i < 16; ++i) { g0[i] = 0.f; g1[i] = 0.f; }
;         if (sb0 <= lb) g0 = mma_nt<4>(lds + S_CC + lb * 32 * LP + 128, lds + S_BC + sb0 * 32 * LP + 128, mma_nt<4>(lds + S_CC + lb * 32 * LP, lds + S_BC + sb0 * 32 * LP, g0, lane), lane);
;         if (sb0 + 1 <= lb) g1 = mma_nt<4>(lds + S_CC + lb * 32 * LP + 128, lds + S_BC + (sb0 + 1) * 32 * LP + 128, mma_nt<4>(lds + S_CC + lb * 32 * LP, lds + S_BC + (sb0 + 1) * 32 * LP, g1, lane), lane);
.LBB0_303:
	s_or_b64 exec, exec, s[0:1]
	v_readlane_b32 s0, v237, 8
	v_readlane_b32 s1, v237, 9
	v_readlane_b32 s2, v237, 10
	s_add_u32 s54, s0, 0x18600000
	s_addc_u32 s55, s1, 0
	s_min_i32 s0, s2, 0x80
	v_readlane_b32 s3, v237, 11
	v_writelane_b32 v237, s0, 60
	s_cmp_ge_i32 s88, s0
	s_waitcnt lgkmcnt(0)
	s_barrier
	v_writelane_b32 v237, s62, 61
	s_cbranch_scc1 .LBB0_354
	v_writelane_b32 v237, s71, 62
	s_lshl_b32 s0, s63, 3
	v_writelane_b32 v237, s89, 63
	v_writelane_b32 v236, s70, 0
	s_and_b32 s85, s51, 0xffff
	s_and_b32 s11, s0, 0x1fffffe0
	s_and_b32 s89, s55, 0xffff
	v_writelane_b32 v236, s71, 1
	s_cmp_lg_u32 s63, 7
	v_ashrrev_i32_e32 v162, 4, v152
	s_movk_i32 s1, 0x5840
	v_writelane_b32 v236, s54, 2
	s_cselect_b64 s[78:79], -1, 0
	s_cmp_eq_u32 s63, 7
	v_mul_lo_u32 v163, v162, s1
	v_writelane_b32 v236, s55, 3
	s_cselect_b64 s[0:1], -1, 0
	v_writelane_b32 v236, s0, 4
	v_lshlrev_b32_e32 v126, 1, v152
	v_or_b32_e32 v127, 1, v126
	v_writelane_b32 v236, s1, 5
	s_movk_i32 s0, 0x80
	v_cmp_gt_i32_e64 s[0:1], s0, v127
	v_mov_b32_e32 v8, 0x7f
	s_add_i32 s9, 0, 0x26800
	v_writelane_b32 v236, s0, 6
	s_lshl_b32 s81, s63, 4
	s_lshl_b32 s98, s63, 2
	s_lshr_b32 s98, 0x50317642, s98
	s_and_b32 s98, s98, 7
	s_lshr_b32 s8, s98, 1
	v_writelane_b32 v236, s1, 7
	v_cmp_gt_i32_e64 s[0:1], 64, v152
	v_ashrrev_i32_e32 v1, 5, v152
	s_movk_i32 s13, 0x880
	v_writelane_b32 v236, s0, 8
	v_mul_lo_u32 v10, v1, s13
	v_bfe_u32 v3, v181, 4, 1
	v_writelane_b32 v236, s1, 9
	v_cndmask_b32_e64 v130, v8, v126, s[0:1]
	v_lshlrev_b32_e32 v8, 3, v152
	s_add_i32 s0, 0, 0x26400
	v_add_u32_e32 v170, s0, v8
	s_lshl_b32 s0, s98, 1
	s_and_b32 s0, s0, 2
	s_cmp_le_u32 s0, s8
	s_cselect_b64 s[4:5], -1, 0
	s_or_b32 s1, s0, 1
	s_cmp_lt_u32 s0, s8
	s_cselect_b64 s[96:97], -1, 0
	s_cmp_ge_u32 s0, s8
	s_cselect_b64 s[70:71], -1, 0
	s_lshl_b32 s10, s8, 5
	s_lshl_b32 s33, s8, 7
	s_add_i32 s6, s10, -1
	s_cmp_gt_u32 s8, 0
	s_cselect_b32 s6, s6, 0
	s_lshl_b32 s13, s63, 5
	v_and_b32_e32 v6, 31, v152
	s_and_b32 s13, s13, 0x60
	v_and_b32_e32 v7, 15, v181
	v_lshrrev_b32_e32 v122, 3, v181
	v_add_u32_e32 v171, s9, v8
	v_mov_b32_e32 v8, 0x8800
	v_cmp_eq_u32_e32 vcc, 0, v3
	v_or_b32_e32 v11, s13, v6
	s_mul_i32 s13, s8, 0x2200
	s_mul_i32 s14, s0, 0x2200
	v_lshlrev_b32_e32 v0, 8, v3
	v_lshlrev_b32_e32 v2, 3, v7
	v_add_u32_e32 v169, 64, v122
	v_cndmask_b32_e32 v3, 0, v8, vcc
	v_lshlrev_b32_e32 v7, 4, v7
	v_lshlrev_b32_e32 v11, 1, v11
	s_add_i32 s13, s13, 0
	s_add_i32 s14, s14, 0
	v_lshlrev_b32_e32 v15, 2, v1
	v_add3_u32 v3, 0, v3, v7
	v_lshrrev_b32_e32 v7, 2, v181
	s_add_i32 s12, 0, 0x1dc00
	v_add3_u32 v173, 0, v10, v11
	v_mov_b32_e32 v10, s13
	s_add_i32 s13, s14, 0x2200
	v_add_u32_e32 v16, s10, v15
	s_add_i32 s10, 0, 0x11000
	v_lshrrev_b32_e32 v22, 6, v181
	v_lshrrev_b32_e32 v25, 3, v169
	v_and_b32_e32 v7, 14, v7
	v_or_b32_e32 v8, s11, v6
	s_movk_i32 s7, 0x110
	s_cmp_ge_u32 s1, s8
	v_bitop3_b32 v22, v22, v181, 7 bitop3:0x78
	v_bitop3_b32 v25, v25, v181, 7 bitop3:0x78
	v_mul_lo_u32 v9, v8, s7
	v_mov_b32_e32 v14, s13
	v_lshl_or_b32 v175, s0, 5, v6
	v_lshl_or_b32 v176, s1, 5, v6
	s_cselect_b64 s[0:1], -1, 0
	v_and_b32_e32 v19, -16, v152
	s_add_i32 s13, 0, 0x22000
	v_add_u32_e32 v15, s11, v15
	v_lshl_or_b32 v22, v22, 4, v7
	s_add_i32 s11, 0, 0x19800
	v_lshl_or_b32 v7, v25, 4, v7
	v_add_u32_e32 v31, 9, v16
	v_writelane_b32 v236, s68, 10
	v_add_u32_e32 v9, s12, v9
	v_add_u32_e32 v20, s13, v19
	v_add_u32_e32 v11, s13, v11
	v_add_u32_e32 v23, s11, v22
	v_add_u32_e32 v22, s12, v22
	v_add_u32_e32 v25, s11, v7
	v_add_u32_e32 v7, s12, v7
	v_cmp_gt_i32_e64 s[12:13], v176, v31
	v_add_u32_e32 v32, 10, v16
	v_add_u32_e32 v33, 11, v16
	v_writelane_b32 v236, s12, 11
	v_add_u32_e32 v34, 16, v16
	v_add_u32_e32 v35, 17, v16
	v_writelane_b32 v236, s13, 12
	v_cmp_gt_i32_e64 s[12:13], v176, v32
	v_cmp_gt_i32_e64 s[28:29], v175, v33
	v_add_u32_e32 v36, 18, v16
	v_writelane_b32 v236, s12, 13
	v_and_b32_e32 v5, 15, v152
	v_lshl_add_u32 v179, v122, 2, s9
	v_writelane_b32 v236, s13, 14
	v_cmp_gt_i32_e64 s[12:13], v176, v33
	v_sub_u32_e32 v33, 0x10ff, v181
	v_lshrrev_b32_e32 v132, 9, v33
	v_writelane_b32 v236, s12, 15
	v_add_u32_e32 v33, 2, v132
	s_movk_i32 s9, 0x440
	v_writelane_b32 v236, s13, 16
	v_cmp_gt_i32_e64 s[12:13], v176, v34
	v_and_b32_e32 v185, 30, v33
	v_mov_b32_e32 v33, s11
	v_writelane_b32 v236, s12, 17
	v_lshrrev_b32_e32 v8, 3, v8
	v_or_b32_e32 v27, 1, v16
	v_writelane_b32 v236, s13, 18
	v_cmp_gt_i32_e64 s[12:13], v176, v35
	v_or_b32_e32 v28, 2, v16
	v_or_b32_e32 v29, 3, v16
	v_writelane_b32 v236, s12, 19
	v_add_u32_e32 v30, 8, v16
	v_mad_u32_u24 v186, v5, s9, v33
	v_writelane_b32 v236, s13, 20
	v_cmp_gt_i32_e64 s[12:13], v176, v36
	s_mul_i32 s9, s63, 0x1100
	s_mov_b32 s74, s88
	v_writelane_b32 v236, s12, 21
	v_lshlrev_b32_e32 v172, 4, v1
	v_mov_b32_e32 v13, s14
	v_writelane_b32 v236, s13, 22
	v_or_b32_e32 v18, s81, v5
	v_cmp_gt_i32_e64 s[36:37], v175, v16
	v_mul_lo_u32 v26, v16, s7
	v_cmp_gt_i32_e64 s[38:39], v175, v27
; #define LAS __attribute__((address_space(3)))
; __device__ __forceinline__ void ssd_item(const Params& P, LAS unsigned char* lds, int item, int tid, int wave, int lane) {
;     ...
;     const int r = lane & 31, hh = lane >> 5;
;     const int xrow0 = tid >> 3, xoct = tid & 7;
;     const int brow0 = tid >> 5, bsel = (tid >> 4) & 1, boct = tid & 15;
;     const int yb = wave & 3, pb = wave >> 2;
;     const int ycol = h * 64 + pb * 32 + r;
;     const __amdgpu_buffer_rsrc_t prs = __builtin_amdgcn_make_buffer_rsrc((void*)PROJ, 0, 0x7fffffff, 0x00020000);
;     const __amdgpu_buffer_rsrc_t yrs = __builtin_amdgcn_make_buffer_rsrc((void*)YS, 0, 0x7fffffff, 0x00020000);
;     const int yc = lane & 15, yg = lane >> 4;
;     const unsigned zvoff = (unsigned)(4 * yg * LDP + OFF_Z + h * 64 + 4 * yc) * 2u, xvoff = (unsigned)(4 * yg * LDP + OFF_XBC + h * 64 + 4 * yc) * 2u, yvoff = (unsigned)(4 * yg * 1024 + h * 64 + 4 * yc) * 2u;
;     f32x16 sacc; for (int i = 0; i < 16; ++i) sacc[i] = 0.f;
;     for (int i = tid; i < 64 * LP / 4; i += NTHR) ((LAS unsigned*)(lds + S_SB))[i] = 0u;
;     const size_t rowbase = (size_t)b * LL;
;     ...
;                 const int nks = (wave >> 1) + 1;
;                 for (int ks = 0; ks < nks; ++ks) {
	v_cmp_gt_i32_e64 s[40:41], v175, v28
	v_cmp_gt_i32_e64 s[42:43], v175, v29
	v_cmp_gt_i32_e64 s[22:23], v175, v30
	v_cmp_gt_i32_e64 s[24:25], v175, v31
	v_cmp_gt_i32_e64 s[26:27], v175, v32
	v_add_u32_e32 v37, 19, v16
	v_add_u32_e32 v38, 24, v16
	v_add_u32_e32 v39, 25, v16
	v_add_u32_e32 v40, 26, v16
	v_add_u32_e32 v41, 27, v16
	v_cmp_gt_i32_e64 s[58:59], v176, v16
	v_cmp_gt_i32_e64 s[60:61], v176, v27
	v_cmp_gt_i32_e64 s[64:65], v176, v28
	v_cmp_gt_i32_e64 s[66:67], v176, v29
	v_cmp_gt_i32_e64 s[92:93], v176, v30
	v_bitop3_b32 v16, v8, v1, 7 bitop3:0x6c
	v_add_u32_e32 v27, 2, v1
	v_add_u32_e32 v28, 4, v1
	v_add_u32_e32 v29, 6, v1
	v_add_u32_e32 v30, 8, v1
	v_add_u32_e32 v31, 10, v1
	v_add_u32_e32 v32, 12, v1
	v_add_u32_e32 v1, 14, v1
	v_writelane_b32 v236, s63, 23
	v_mov_b32_e32 v33, s9
	v_lshlrev_b32_e32 v164, 2, v5
	v_mad_u32_u24 v10, v6, s7, v10
	v_mad_u32_u24 v13, v6, s7, v13
	v_mad_u32_u24 v14, v6, s7, v14
	v_mul_lo_u32 v18, v18, s7
	v_bitop3_b32 v27, v8, v27, 7 bitop3:0x6c
	v_bitop3_b32 v28, v8, v28, 7 bitop3:0x6c
	v_bitop3_b32 v29, v8, v29, 7 bitop3:0x6c
	v_bitop3_b32 v30, v8, v30, 7 bitop3:0x6c
	v_bitop3_b32 v31, v8, v31, 7 bitop3:0x6c
	v_bitop3_b32 v32, v8, v32, 7 bitop3:0x6c
	v_bitop3_b32 v1, v8, v1, 7 bitop3:0x6c
	v_mul_u32_u24_e32 v8, 0x440, v5
	v_mul_lo_u32 v15, v15, s7
	v_mad_u32_u24 v5, v5, s7, v33
	s_lshl_b32 s12, s6, 2
	v_writelane_b32 v236, s74, 24
	v_cmp_gt_i32_e64 s[6:7], v176, v37
	v_lshrrev_b32_e32 v104, 5, v181
	v_lshlrev_b32_e32 v167, 2, v162
	v_writelane_b32 v236, s6, 25
	v_ashrrev_i32_e32 v12, 1, v152
	v_mov_b32_e32 v107, 0
	v_writelane_b32 v236, s7, 26
	v_cmp_gt_i32_e64 s[6:7], v176, v38
	v_add_u32_e32 v168, 0x70, v104
	v_lshlrev_b32_e32 v4, 3, v154
	v_writelane_b32 v236, s6, 27
	s_mov_b32 s2, 0
	v_min_i32_e32 v128, 0x7f, v127
	v_writelane_b32 v236, s7, 28
	v_cmp_gt_i32_e64 s[6:7], v176, v39
	v_and_b32_e32 v12, -16, v12
	v_lshl_add_u32 v17, v175, 1, s10
	v_writelane_b32 v236, s6, 29
	v_lshl_add_u32 v6, v176, 1, s10
	v_add_u32_e32 v18, 0, v18
	v_writelane_b32 v236, s7, 30
	v_cmp_gt_i32_e64 s[6:7], v176, v40
	v_add_u32_e32 v178, s81, v167
	v_mul_u32_u24_e32 v21, 0x110, v104
	v_writelane_b32 v236, s6, 31
	v_mul_u32_u24_e32 v24, 0x880, v154
	v_lshlrev_b32_e32 v16, 4, v16
	v_writelane_b32 v236, s7, 32
	v_cmp_gt_i32_e64 s[6:7], v176, v41
	v_lshlrev_b32_e32 v27, 4, v27
	v_lshlrev_b32_e32 v28, 4, v28
	v_writelane_b32 v236, s6, 33
	v_lshlrev_b32_e32 v29, 4, v29
	v_lshlrev_b32_e32 v30, 4, v30
	v_lshlrev_b32_e32 v31, 4, v31
	v_lshlrev_b32_e32 v32, 4, v32
	v_lshlrev_b32_e32 v1, 4, v1
	v_lshlrev_b32_e32 v106, 4, v154
	v_writelane_b32 v236, s7, 34
	s_mov_b32 s84, s50
	s_mov_b32 s87, 0x20000
	s_brev_b32 s86, -2
	v_or_b32_e32 v165, 0x400, v164
	v_lshl_or_b32 v166, v162, 12, v164
	v_mov_b32_e32 v105, v107
	v_add_u32_e32 v108, 16, v104
	v_mov_b32_e32 v109, v107
	v_or_b32_e32 v110, 32, v104
	v_mov_b32_e32 v111, v107
	v_add_u32_e32 v112, 48, v104
	v_mov_b32_e32 v113, v107
	v_or_b32_e32 v114, 64, v104
	v_mov_b32_e32 v115, v107
	v_add_u32_e32 v116, 0x50, v104
	v_mov_b32_e32 v117, v107
	v_or_b32_e32 v118, 0x60, v104
	v_mov_b32_e32 v119, v107
	v_min_u32_e32 v120, 0x7f, v168
	v_mov_b32_e32 v121, v107
	s_mov_b32 s88, s54
	v_mov_b32_e32 v123, v107
	v_min_u32_e32 v124, 0x7f, v169
	v_mov_b32_e32 v125, v107
	s_mov_b32 s3, 1
	v_ashrrev_i32_e32 v129, 31, v128
	v_ashrrev_i32_e32 v131, 31, v130
	v_add_u32_e32 v174, 0x8800, v173
	v_bfe_u32 v177, v152, 1, 3
	v_cmp_gt_i32_e64 s[30:31], v175, v34
	v_cmp_gt_i32_e64 s[34:35], v175, v35
	v_cmp_gt_i32_e64 s[44:45], v175, v36
	v_cmp_gt_i32_e64 s[46:47], v175, v37
	v_cmp_gt_i32_e64 s[48:49], v175, v38
	v_cmp_gt_i32_e64 s[52:53], v175, v39
	v_cmp_gt_i32_e64 s[54:55], v175, v40
	v_cmp_gt_i32_e64 s[56:57], v175, v41
	v_or_b32_e32 v182, 1, v178
	v_or_b32_e32 v183, 2, v178
	v_or_b32_e32 v184, 3, v178
	v_mov_b32_e32 v133, v132
	v_lshl_add_u64 v[134:135], s[50:51], 0, v[106:107]
	v_add_u32_e32 v153, 0x22800, v153
	s_lshr_b32 s8, s63, 1
	s_add_i32 s8, s8, 1
	v_add3_u32 v187, v5, v19, s10
	s_movk_i32 s9, 0x1000
	s_movk_i32 s10, 0x2c20
	v_lshlrev_b32_e32 v106, 1, v0
	v_lshlrev_b32_e32 v136, 1, v2
	v_lshlrev_b32_e32 v138, 1, v4
	s_mov_b32 s11, 0xbfb8aa3b
	v_add_u32_e32 v188, v3, v21
	v_add_u32_e32 v189, v23, v24
	v_add_u32_e32 v190, v22, v24
	v_add_u32_e32 v191, v25, v24
	v_add_u32_e32 v192, v7, v24
	v_add_u32_e32 v193, v13, v12
	v_add_u32_e32 v194, v14, v12
	v_add_u32_e32 v195, v9, v16
	v_add_u32_e32 v196, v9, v27
	v_add_u32_e32 v197, v9, v28
	v_add_u32_e32 v198, v9, v29
	s_mov_b32 s13, 0x5040100
	v_add_u32_e32 v199, v9, v30
	v_add_u32_e32 v200, v9, v31
	v_add_u32_e32 v201, v9, v32
	v_add_u32_e32 v202, v9, v1
	v_add_u32_e32 v203, v18, v19
	v_add_u32_e32 v204, v20, v8
	v_add_u32_e32 v205, v11, v15
	v_mov_b32_e32 v206, 0x1010
	v_add_u32_e32 v207, v10, v12
	v_add_u32_e32 v208, v17, v26
	v_add_u32_e32 v209, v6, v26
	s_mov_b32 s82, s74
	v_writelane_b32 v236, s0, 35
	s_nop 1
	v_writelane_b32 v236, s1, 36
	s_branch .LBB0_306

; #define LAS __attribute__((address_space(3)))
; __device__ __forceinline__ void ssd_item(const Params& P, LAS unsigned char* lds, int item, int tid, int wave, int lane) {
;     ...
;     for (int c = 0; c < 33; ++c) {
;         const int p0 = 128 * c, nvalid = (LL - p0) < 128 ? (LL - p0) : 128;
;         LAS float* ACS = (LAS float*)(lds + S_ACS) + (c & 1) * 128; LAS float* DTV = (LAS float*)(lds + S_DTV) + (c & 1) * 128;
; #pragma unroll
;         for (int k = 0; k < 8; ++k) { const int br = brow0 + 16 * k;
;             u32x4 v = pbc[k]; if (br >= nvalid) v = (u32x4){0u, 0u, 0u, 0u};
;             *(LAS u32x4*)(lds + (bsel ? S_CC : S_BC) + br * LP + boct * 16) = v; }
;     ...
;         u32x2 zc[4], xc[4];
;         {
;             const int zb = __builtin_amdgcn_readfirstlane((int)(((unsigned)rowbase + p0 + wave * 16) * LDP * 2u));
; #pragma unroll
;             for (int i = 0; i < 4; ++i) { zc[i] = __builtin_bit_cast(u32x2, __builtin_amdgcn_raw_buffer_load_b64(prs, zvoff, zb + i * (LDP * 2), 2));
;                                           xc[i] = __builtin_bit_cast(u32x2, __builtin_amdgcn_raw_buffer_load_b64(prs, xvoff, zb + i * (LDP * 2), 2)); }
;         }
.LBB0_318:
	s_waitcnt vmcnt(4)
	s_lshl_b32 s98, s17, 7
	s_add_i32 s98, s98, s16
	s_mul_i32 s98, s98, 0x2c20
	s_add_i32 s99, s98, 0x2c20
	s_add_i32 s100, s98, 0x5840
	s_add_i32 s101, s98, 0x8460
	buffer_load_dwordx2 v[160:161], v214, s[84:87], s98 offen nt
	buffer_load_dwordx2 v[156:157], v214, s[84:87], s99 offen nt
	buffer_load_dwordx2 v[150:151], v214, s[84:87], s100 offen nt
	buffer_load_dwordx2 v[144:145], v214, s[84:87], s101 offen nt
	buffer_load_dwordx2 v[158:159], v213, s[84:87], s98 offen nt
	buffer_load_dwordx2 v[154:155], v213, s[84:87], s99 offen nt
	buffer_load_dwordx2 v[148:149], v213, s[84:87], s100 offen nt
	buffer_load_dwordx2 v[146:147], v213, s[84:87], s101 offen nt
	s_lshl_b32 s6, s17, 7
	s_sub_i32 s7, 0x1010, s6
	s_min_u32 s19, s7, 0x80
	v_cmp_gt_u32_e32 vcc, s19, v104
	s_lshl_b32 s7, s17, 9
	s_and_b32 s7, s7, 0x200
	v_cndmask_b32_e32 v19, 0, v51, vcc
	v_cndmask_b32_e32 v18, 0, v50, vcc
	v_cndmask_b32_e32 v17, 0, v49, vcc
	v_cndmask_b32_e32 v16, 0, v48, vcc
	v_cmp_gt_u32_e32 vcc, s19, v108
	ds_write_b128 v188, v[16:19]
	s_add_i32 s21, s7, 0
	v_cndmask_b32_e32 v19, 0, v55, vcc
	v_cndmask_b32_e32 v18, 0, v54, vcc
	v_cndmask_b32_e32 v17, 0, v53, vcc
	v_cndmask_b32_e32 v16, 0, v52, vcc
	v_cmp_gt_u32_e32 vcc, s19, v110
	ds_write_b128 v188, v[16:19] offset:4352
	s_add_i32 s21, s21, 0x26400
	v_cndmask_b32_e32 v19, 0, v59, vcc
	v_cndmask_b32_e32 v18, 0, v58, vcc
	v_cndmask_b32_e32 v17, 0, v57, vcc
	v_cndmask_b32_e32 v16, 0, v56, vcc
	v_cmp_gt_u32_e32 vcc, s19, v112
	ds_write_b128 v188, v[16:19] offset:8704
	v_lshlrev_b32_e32 v21, 16, v80
	v_cndmask_b32_e32 v19, 0, v63, vcc
	v_cndmask_b32_e32 v18, 0, v62, vcc
	v_cndmask_b32_e32 v17, 0, v61, vcc
	v_cndmask_b32_e32 v16, 0, v60, vcc
	v_cmp_gt_u32_e32 vcc, s19, v114
	ds_write_b128 v188, v[16:19] offset:13056
	s_add_i32 s20, s16, s6
	v_cndmask_b32_e32 v19, 0, v67, vcc
	v_cndmask_b32_e32 v18, 0, v66, vcc
	v_cndmask_b32_e32 v17, 0, v65, vcc
	v_cndmask_b32_e32 v16, 0, v64, vcc
	v_cmp_gt_u32_e32 vcc, s19, v116
	ds_write_b128 v188, v[16:19] offset:17408
	s_mul_i32 s6, s20, 0x2c20
	v_cndmask_b32_e32 v19, 0, v71, vcc
	v_cndmask_b32_e32 v18, 0, v70, vcc
	v_cndmask_b32_e32 v17, 0, v69, vcc
	v_cndmask_b32_e32 v16, 0, v68, vcc
	v_cmp_gt_u32_e32 vcc, s19, v118
	ds_write_b128 v188, v[16:19] offset:21760
	s_add_i32 s18, s6, 0x5840
	v_cndmask_b32_e32 v19, 0, v75, vcc
	v_cndmask_b32_e32 v18, 0, v74, vcc
	v_cndmask_b32_e32 v17, 0, v73, vcc
	v_cndmask_b32_e32 v16, 0, v72, vcc
	v_cmp_gt_u32_e32 vcc, s19, v168
	ds_write_b128 v188, v[16:19] offset:26112
	s_add_i32 s74, s6, 0x8460
	v_cndmask_b32_e32 v19, 0, v79, vcc
	v_cndmask_b32_e32 v18, 0, v78, vcc
	v_cndmask_b32_e32 v17, 0, v77, vcc
	v_cndmask_b32_e32 v16, 0, v76, vcc
	ds_write_b128 v188, v[16:19] offset:30464
	v_mov_b32_e32 v16, s21
	ds_read_b32 v20, v16 offset:508
	v_lshl_add_u32 v16, v122, 2, s21
	ds_read2st64_b32 v[16:17], v16 offset1:1
	v_add_u32_e32 v18, s7, v179
	ds_read2st64_b32 v[18:19], v18 offset1:1
	v_cmp_gt_u32_e32 vcc, s19, v122
	s_add_i32 s7, s6, 0x2c20
	s_waitcnt lgkmcnt(1)
	v_sub_f32_e32 v16, v20, v16
	v_mul_f32_e32 v16, 0x3fb8aa3b, v16
	v_exp_f32_e32 v16, v16
	v_cndmask_b32_e32 v21, 0, v21, vcc
	s_waitcnt lgkmcnt(0)
; #define LAS __attribute__((address_space(3)))
; __device__ __forceinline__ unsigned f2bf(float f) { return pk2(f, 0.f) & 0xffffu; }
; __device__ __forceinline__ float fexp(float x) { return __builtin_amdgcn_exp2f(x * 1.4426950408889634f); }
; __device__ __forceinline__ void ssd_item(const Params& P, LAS unsigned char* lds, int item, int tid, int wave, int lane) {
;     ...
;         {
;             const float aend = ACS[127];
; #pragma unroll
;             for (int q = 0; q < 2; ++q) { const int s = xrow0 + 64 * q; const bool sv = s < nvalid;
;                 const float dtv = DTV[s], dd = fexp(aend - ACS[s]);
;                 const unsigned w4[4] = {pxv[q].x, pxv[q].y, pxv[q].z, pxv[q].w};
;                 const int sofs = (((s >> 3) ^ xoct) << 4) + (s & 7) * 2;
; #pragma unroll
;                 for (int j = 0; j < 8; ++j) { float x = (j & 1) ? bfhi(w4[j >> 1]) : bflo(w4[j >> 1]); x = sv ? x : 0.f; const int p = xoct * 8 + j;
;                     const float xd = x * dtv;
;                     *(LAS unsigned short*)(lds + S_XDTT + p * LP + sofs) = (unsigned short)f2bf(xd);
;                     *(LAS unsigned short*)(lds + S_XDDT + p * LP + sofs) = (unsigned short)f2bf(xd * dd); } }
;         }
;         __syncthreads();
	v_mul_f32_e32 v21, v21, v18
	v_cvt_pk_bf16_f32 v22, v21, s0
	v_mul_f32_e32 v21, v21, v16
	v_cvt_pk_bf16_f32 v21, v21, s0
	ds_write_b16 v190, v21
	v_and_b32_e32 v21, 0xffff0000, v80
	v_cndmask_b32_e32 v21, 0, v21, vcc
	v_mul_f32_e32 v21, v21, v18
	ds_write_b16 v189, v22
	v_cvt_pk_bf16_f32 v22, v21, s0
	v_mul_f32_e32 v21, v21, v16
	v_cvt_pk_bf16_f32 v21, v21, s0
	ds_write_b16 v190, v21 offset:272
	v_lshlrev_b32_e32 v21, 16, v81
	v_cndmask_b32_e32 v21, 0, v21, vcc
	v_mul_f32_e32 v21, v21, v18
	ds_write_b16 v189, v22 offset:272
	v_cvt_pk_bf16_f32 v22, v21, s0
	v_mul_f32_e32 v21, v21, v16
	v_cvt_pk_bf16_f32 v21, v21, s0
	ds_write_b16 v190, v21 offset:544
	v_and_b32_e32 v21, 0xffff0000, v81
	v_cndmask_b32_e32 v21, 0, v21, vcc
	v_mul_f32_e32 v21, v21, v18
	ds_write_b16 v189, v22 offset:544
	v_cvt_pk_bf16_f32 v22, v21, s0
	v_mul_f32_e32 v21, v21, v16
	v_cvt_pk_bf16_f32 v21, v21, s0
	ds_write_b16 v190, v21 offset:816
	v_lshlrev_b32_e32 v21, 16, v82
	v_cndmask_b32_e32 v21, 0, v21, vcc
	v_mul_f32_e32 v21, v21, v18
	ds_write_b16 v189, v22 offset:816
	v_cvt_pk_bf16_f32 v22, v21, s0
	v_mul_f32_e32 v21, v21, v16
	v_cvt_pk_bf16_f32 v21, v21, s0
	ds_write_b16 v190, v21 offset:1088
	v_and_b32_e32 v21, 0xffff0000, v82
	v_cndmask_b32_e32 v21, 0, v21, vcc
	v_mul_f32_e32 v21, v21, v18
	ds_write_b16 v189, v22 offset:1088
	v_cvt_pk_bf16_f32 v22, v21, s0
	v_mul_f32_e32 v21, v21, v16
	v_cvt_pk_bf16_f32 v21, v21, s0
	ds_write_b16 v190, v21 offset:1360
	v_lshlrev_b32_e32 v21, 16, v83
	v_cndmask_b32_e32 v21, 0, v21, vcc
	v_mul_f32_e32 v21, v21, v18
	ds_write_b16 v189, v22 offset:1360
	v_cvt_pk_bf16_f32 v22, v21, s0
	v_mul_f32_e32 v21, v21, v16
	v_cvt_pk_bf16_f32 v21, v21, s0
	ds_write_b16 v190, v21 offset:1632
	v_and_b32_e32 v21, 0xffff0000, v83
	v_cndmask_b32_e32 v21, 0, v21, vcc
	v_mul_f32_e32 v18, v21, v18
	v_mul_f32_e32 v16, v18, v16
	v_cvt_pk_bf16_f32 v16, v16, s0
	ds_write_b16 v190, v16 offset:1904
	v_sub_f32_e32 v16, v20, v17
	v_mul_f32_e32 v16, 0x3fb8aa3b, v16
	v_exp_f32_e32 v16, v16
	v_lshlrev_b32_e32 v17, 16, v84
	v_cmp_gt_u32_e32 vcc, s19, v169
	v_cvt_pk_bf16_f32 v21, v18, s0
	ds_write_b16 v189, v22 offset:1632
	v_cndmask_b32_e32 v17, 0, v17, vcc
	v_mul_f32_e32 v17, v17, v19
	v_cvt_pk_bf16_f32 v18, v17, s0
	v_mul_f32_e32 v17, v17, v16
	v_cvt_pk_bf16_f32 v17, v17, s0
	ds_write_b16 v192, v17
	v_and_b32_e32 v17, 0xffff0000, v84
	v_cndmask_b32_e32 v17, 0, v17, vcc
	v_mul_f32_e32 v17, v17, v19
	ds_write_b16 v189, v21 offset:1904
	ds_write_b16 v191, v18
	v_cvt_pk_bf16_f32 v18, v17, s0
	v_mul_f32_e32 v17, v17, v16
	v_cvt_pk_bf16_f32 v17, v17, s0
	ds_write_b16 v192, v17 offset:272
	v_lshlrev_b32_e32 v17, 16, v85
	v_cndmask_b32_e32 v17, 0, v17, vcc
	v_mul_f32_e32 v17, v17, v19
	ds_write_b16 v191, v18 offset:272
	v_cvt_pk_bf16_f32 v18, v17, s0
	v_mul_f32_e32 v17, v17, v16
	v_cvt_pk_bf16_f32 v17, v17, s0
	ds_write_b16 v192, v17 offset:544
	v_and_b32_e32 v17, 0xffff0000, v85
	v_cndmask_b32_e32 v17, 0, v17, vcc
	v_mul_f32_e32 v17, v17, v19
	ds_write_b16 v191, v18 offset:544
	v_cvt_pk_bf16_f32 v18, v17, s0
	v_mul_f32_e32 v17, v17, v16
	v_cvt_pk_bf16_f32 v17, v17, s0
	ds_write_b16 v192, v17 offset:816
	v_lshlrev_b32_e32 v17, 16, v86
	v_cndmask_b32_e32 v17, 0, v17, vcc
	v_mul_f32_e32 v17, v17, v19
	ds_write_b16 v191, v18 offset:816
	v_cvt_pk_bf16_f32 v18, v17, s0
	v_mul_f32_e32 v17, v17, v16
	v_cvt_pk_bf16_f32 v17, v17, s0
	ds_write_b16 v192, v17 offset:1088
	v_and_b32_e32 v17, 0xffff0000, v86
	v_cndmask_b32_e32 v17, 0, v17, vcc
	v_mul_f32_e32 v17, v17, v19
	ds_write_b16 v191, v18 offset:1088
	v_cvt_pk_bf16_f32 v18, v17, s0
	v_mul_f32_e32 v17, v17, v16
	v_cvt_pk_bf16_f32 v17, v17, s0
	ds_write_b16 v192, v17 offset:1360
	v_lshlrev_b32_e32 v17, 16, v87
	v_cndmask_b32_e32 v17, 0, v17, vcc
	v_mul_f32_e32 v17, v17, v19
	ds_write_b16 v191, v18 offset:1360
	v_cvt_pk_bf16_f32 v18, v17, s0
	v_mul_f32_e32 v17, v17, v16
	v_cvt_pk_bf16_f32 v17, v17, s0
	ds_write_b16 v192, v17 offset:1632
	v_and_b32_e32 v17, 0xffff0000, v87
	v_cndmask_b32_e32 v17, 0, v17, vcc
	v_mul_f32_e32 v17, v17, v19
	v_mul_f32_e32 v16, v17, v16
	ds_write_b16 v191, v18 offset:1632
	v_cvt_pk_bf16_f32 v18, v17, s0
	v_cvt_pk_bf16_f32 v16, v16, s0
	ds_write_b16 v191, v18 offset:1904
	ds_write_b16 v192, v16 offset:1904
	s_waitcnt lgkmcnt(0)
	s_barrier
	s_add_i32 s18, s17, 1
	s_cmp_eq_u32 s17, 32
	s_cselect_b64 s[6:7], -1, 0
	s_and_b64 vcc, exec, s[6:7]
	s_cbranch_vccnz .LBB0_321

; #define LAS __attribute__((address_space(3)))
; __device__ __forceinline__ void ssd_item(const Params& P, LAS unsigned char* lds, int item, int tid, int wave, int lane) {
;     ...
;                 const LAS unsigned char* map = lds + S_MM + (wave * 16 + yc) * LP + yg * 16;
;                 const int nks = (wave >> 1) + 1;
;                 for (int ks = 0; ks < nks; ++ks) {
;                     const bf16x8 am = *(const LAS bf16x8*)(map + ks * 64);
; #pragma unroll
;                     for (int q = 0; q < 4; ++q) { const int p = 4 * yc + q; const int xsw = (p >> 3) & 7;
;                         const bf16x8 bx = *(const LAS bf16x8*)(lds + S_XDTT + p * LP + (((4 * ks + yg) ^ xsw) << 4));
;                         ya[q] = __builtin_amdgcn_mfma_f32_16x16x32_bf16(am, bx, ya[q], 0, 0, 0); }
;                 }
.LBB0_336:
	ds_read_b128 v[98:101], v96
	v_xor_b32_e32 v102, v97, v177
	v_lshl_add_u32 v102, v102, 4, v186
	ds_read_b128 v[216:219], v102
	s_add_i32 s21, s21, -1
	v_add_u32_e32 v97, 4, v97
	v_add_u32_e32 v96, 64, v96
	s_cmp_eq_u32 s21, 0
	s_waitcnt lgkmcnt(0)
	v_mfma_f32_16x16x32_bf16 v[24:27], v[98:101], v[216:219], v[24:27]
	ds_read_b128 v[216:219], v102 offset:272
	s_waitcnt lgkmcnt(0)
	v_mfma_f32_16x16x32_bf16 v[28:31], v[98:101], v[216:219], v[28:31]
	ds_read_b128 v[216:219], v102 offset:544
	s_waitcnt lgkmcnt(0)
	v_mfma_f32_16x16x32_bf16 v[16:19], v[98:101], v[216:219], v[16:19]
	ds_read_b128 v[216:219], v102 offset:816
	s_waitcnt lgkmcnt(0)
	v_mfma_f32_16x16x32_bf16 v[20:23], v[98:101], v[216:219], v[20:23]
	s_cbranch_scc0 .LBB0_336
	s_and_b64 vcc, exec, s[6:7]
	s_cbranch_vccnz .Lssd_wz
	s_waitcnt vmcnt(10)
	s_branch .Lssd_wd

; __device__ __forceinline__ float silu(float v) { return v * __builtin_amdgcn_rcpf(1.f + fexp(-v)); }
; __device__ __forceinline__ void ssd_item(const Params& P, LAS unsigned char* lds, int item, int tid, int wave, int lane) {
;     ...
;             u32x2 yo[4];
; #pragma unroll
;             for (int i = 0; i < 4; ++i) {
;                 const float z0 = bflo(zc[i].x), z1 = bfhi(zc[i].x), z2 = bflo(zc[i].y), z3 = bfhi(zc[i].y);
;                 const float x0 = bflo(xc[i].x), x1 = bfhi(xc[i].x), x2 = bflo(xc[i].y), x3 = bfhi(xc[i].y);
;                 yo[i].x = pk2((ya[0][i] + Dh * x0) * silu(z0), (ya[1][i] + Dh * x1) * silu(z1));
;                 yo[i].y = pk2((ya[2][i] + Dh * x2) * silu(z2), (ya[3][i] + Dh * x3) * silu(z3)); }
;             __builtin_amdgcn_sched_barrier(0);
;             const int yb0 = __builtin_amdgcn_readfirstlane((int)(((unsigned)rowbase + p0 + wave * 16) * 1024u * 2u));
;             if (nvalid == 128) {
; #pragma unroll
;                 for (int i = 0; i < 4; ++i) __builtin_amdgcn_raw_buffer_store_b64(__builtin_bit_cast(__attribute__((__vector_size__(2 * sizeof(unsigned)))) unsigned, yo[i]), yrs, yvoff, yb0 + i * 2048, 0);
;             } else {
; #pragma unroll
;                 for (int i = 0; i < 4; ++i) if (wave * 16 + 4 * yg + i < nvalid) __builtin_amdgcn_raw_buffer_store_b64(__builtin_bit_cast(__attribute__((__vector_size__(2 * sizeof(unsigned)))) unsigned, yo[i]), yrs, yvoff, yb0 + i * 2048, 0);
;             }
.Lssd_wd:
	v_perm_b32 v99, v92, v90, s13
	v_perm_b32 v98, v89, v88, s13
	v_perm_b32 v97, v47, v46, s13
	v_perm_b32 v96, v45, v44, s13
	v_perm_b32 v45, v95, v94, s13
	v_perm_b32 v44, v93, v91, s13
	v_mfma_f32_32x32x16_bf16 v[0:15], v[36:39], v[96:99], v[0:15]
	v_perm_b32 v43, v43, v42, s13
	v_perm_b32 v42, v41, v40, s13
	v_lshlrev_b32_e32 v36, 16, v160
	v_and_b32_e32 v37, 0xffff0000, v160
	v_mul_f32_e32 v39, 0xbfb8aa3b, v36
	v_exp_f32_e32 v40, v39
	v_lshlrev_b32_e32 v38, 16, v158
	v_mfma_f32_32x32x16_bf16 v[0:15], v[32:35], v[42:45], v[0:15]
	v_mul_f32_e32 v32, 0xbfb8aa3b, v37
	v_exp_f32_e32 v33, v32
	v_add_f32_e32 v32, 1.0, v40
	v_rcp_f32_e32 v32, v32
	v_and_b32_e32 v39, 0xffff0000, v158
	v_add_f32_e32 v33, 1.0, v33
	v_rcp_f32_e32 v33, v33
	v_mov_b32_e32 v34, v24
	v_mov_b32_e32 v35, v28
	v_pk_fma_f32 v[34:35], v[140:141], v[38:39], v[34:35]
	v_pk_mul_f32 v[32:33], v[32:33], v[36:37]
	v_lshlrev_b32_e32 v36, 16, v159
	v_pk_mul_f32 v[32:33], v[32:33], v[34:35]
	v_lshlrev_b32_e32 v34, 16, v161
	v_and_b32_e32 v35, 0xffff0000, v161
	v_mul_f32_e32 v24, 0xbfb8aa3b, v34
	v_exp_f32_e32 v24, v24
	v_mul_f32_e32 v28, 0xbfb8aa3b, v35
	v_exp_f32_e32 v28, v28
	v_and_b32_e32 v37, 0xffff0000, v159
	v_add_f32_e32 v24, 1.0, v24
	v_rcp_f32_e32 v38, v24
	v_add_f32_e32 v24, 1.0, v28
	v_rcp_f32_e32 v39, v24
	v_mov_b32_e32 v40, v16
	v_mov_b32_e32 v41, v20
	v_pk_fma_f32 v[36:37], v[140:141], v[36:37], v[40:41]
	v_pk_mul_f32 v[34:35], v[38:39], v[34:35]
	v_cvt_pk_bf16_f32 v32, v32, v33
	v_pk_mul_f32 v[34:35], v[34:35], v[36:37]
	v_lshlrev_b32_e32 v36, 16, v154
	v_cvt_pk_bf16_f32 v33, v34, v35
	v_lshlrev_b32_e32 v34, 16, v156
	v_and_b32_e32 v35, 0xffff0000, v156
	v_mul_f32_e32 v16, 0xbfb8aa3b, v34
	v_exp_f32_e32 v16, v16
	v_mul_f32_e32 v20, 0xbfb8aa3b, v35
	v_exp_f32_e32 v20, v20
	v_and_b32_e32 v37, 0xffff0000, v154
	v_add_f32_e32 v16, 1.0, v16
	v_rcp_f32_e32 v38, v16
	v_add_f32_e32 v16, 1.0, v20
	v_rcp_f32_e32 v39, v16
	v_mov_b32_e32 v28, v25
	v_pk_fma_f32 v[24:25], v[140:141], v[36:37], v[28:29]
	v_mov_b32_e32 v36, v18
	v_pk_mul_f32 v[28:29], v[38:39], v[34:35]
	v_mov_b32_e32 v37, v22
	v_pk_mul_f32 v[24:25], v[28:29], v[24:25]
	s_nop 0
	v_cvt_pk_bf16_f32 v16, v24, v25
	v_lshlrev_b32_e32 v24, 16, v157
	v_and_b32_e32 v25, 0xffff0000, v157
	v_mul_f32_e32 v20, 0xbfb8aa3b, v24
	v_exp_f32_e32 v20, v20
	v_mul_f32_e32 v28, 0xbfb8aa3b, v25
	v_exp_f32_e32 v29, v28
	v_lshlrev_b32_e32 v28, 16, v155
	v_add_f32_e32 v20, 1.0, v20
	v_rcp_f32_e32 v34, v20
	v_add_f32_e32 v20, 1.0, v29
	v_rcp_f32_e32 v35, v20
	v_and_b32_e32 v29, 0xffff0000, v155
	v_mov_b32_e32 v20, v17
	v_pk_fma_f32 v[20:21], v[140:141], v[28:29], v[20:21]
	v_pk_mul_f32 v[24:25], v[34:35], v[24:25]
	v_mov_b32_e32 v34, v26
	v_pk_mul_f32 v[20:21], v[24:25], v[20:21]
	v_lshlrev_b32_e32 v24, 16, v148
	v_cvt_pk_bf16_f32 v17, v20, v21
	v_lshlrev_b32_e32 v20, 16, v150
	v_and_b32_e32 v21, 0xffff0000, v150
	v_mul_f32_e32 v25, 0xbfb8aa3b, v20
	v_exp_f32_e32 v28, v25
	v_mul_f32_e32 v25, 0xbfb8aa3b, v21
	v_exp_f32_e32 v29, v25
	v_and_b32_e32 v25, 0xffff0000, v148
	v_add_f32_e32 v28, 1.0, v28
	v_rcp_f32_e32 v28, v28
	v_add_f32_e32 v29, 1.0, v29
	v_rcp_f32_e32 v29, v29
	v_mov_b32_e32 v35, v30
	v_pk_fma_f32 v[24:25], v[140:141], v[24:25], v[34:35]
	v_pk_mul_f32 v[20:21], v[28:29], v[20:21]
	s_nop 0
	v_pk_mul_f32 v[20:21], v[20:21], v[24:25]
	v_lshlrev_b32_e32 v24, 16, v151
	v_cvt_pk_bf16_f32 v20, v20, v21
	v_and_b32_e32 v25, 0xffff0000, v151
	v_mul_f32_e32 v21, 0xbfb8aa3b, v24
	v_exp_f32_e32 v21, v21
	v_mul_f32_e32 v26, 0xbfb8aa3b, v25
	v_exp_f32_e32 v26, v26
	v_lshlrev_b32_e32 v28, 16, v149
	v_add_f32_e32 v21, 1.0, v21
	v_rcp_f32_e32 v34, v21
	v_add_f32_e32 v21, 1.0, v26
	v_rcp_f32_e32 v35, v21
	v_and_b32_e32 v29, 0xffff0000, v149
	v_pk_fma_f32 v[28:29], v[140:141], v[28:29], v[36:37]
	v_pk_mul_f32 v[24:25], v[34:35], v[24:25]
	s_nop 0
	v_pk_mul_f32 v[24:25], v[24:25], v[28:29]
	s_nop 0
	v_cvt_pk_bf16_f32 v21, v24, v25
	s_cmpk_lg_i32 s19, 0x80
	s_cbranch_scc0 .LBB0_345
	v_cmp_gt_i32_e32 vcc, s19, v178
	s_and_saveexec_b64 s[74:75], vcc
	s_cbranch_execz .LBB0_351
	s_lshl_b32 s21, s20, 11
	s_mov_b32 s90, s86
	s_mov_b32 s91, s87
	buffer_store_dwordx2 v[32:33], v215, s[88:91], s21 offen
	s_or_b64 exec, exec, s[74:75]
	v_cmp_gt_i32_e32 vcc, s19, v182
	s_and_saveexec_b64 s[74:75], vcc
	s_cbranch_execnz .LBB0_352

.LBB0_350:
	s_waitcnt vmcnt(4)
	v_lshlrev_b32_e32 v16, 16, v211
	v_lshlrev_b32_e32 v17, 16, v212
	v_add_f32_e32 v16, v210, v16
	v_add_f32_e32 v17, v210, v17
	v_mul_f32_e64 v18, |v16|, s11
	v_mul_f32_e64 v19, |v17|, s11
	v_exp_f32_e32 v18, v18
	v_exp_f32_e32 v19, v19
	s_lshl_b32 s6, s18, 7
	s_sub_i32 s6, 0x1010, s6
	v_add_f32_e32 v18, 1.0, v18
	v_add_f32_e32 v19, 1.0, v19
	v_log_f32_e32 v18, v18
	v_log_f32_e32 v19, v19
	s_cmp_gt_u32 s17, 30
	s_cselect_b32 s6, s6, 0x80
	v_max_f32_e32 v16, 0, v16
	v_max_f32_e32 v17, 0, v17
	s_mov_b32 s20, 0x3f317218
	v_pk_fma_f32 v[16:17], v[18:19], s[20:21], v[16:17] op_sel_hi:[1,0,1]
	v_cmp_gt_i32_e32 vcc, s6, v127
	v_mov_b32_e32 v22, v107
	s_lshl_b32 s7, s18, 9
	v_cndmask_b32_e32 v17, 0, v17, vcc
	v_cmp_gt_i32_e32 vcc, s6, v126
	s_and_b32 s7, s7, 0x200
	v_add_u32_e32 v20, s7, v170
	v_cndmask_b32_e32 v16, 0, v16, vcc
	v_mul_f32_e32 v18, v16, v139
	v_fma_f32 v18, v17, -v139, -v18
	v_add_u32_e32 v21, s7, v171
	s_nop 0
	v_add_f32_dpp v19, v18, v18 row_shr:1 row_mask:0xf bank_mask:0xf bound_ctrl:1
	s_nop 1
	v_add_f32_dpp v19, v19, v19 row_shr:2 row_mask:0xf bank_mask:0xf bound_ctrl:1
	s_nop 1
	v_add_f32_dpp v19, v19, v19 row_shr:4 row_mask:0xf bank_mask:0xf bound_ctrl:1
	s_nop 1
	v_add_f32_dpp v19, v19, v19 row_shr:8 row_mask:0xf bank_mask:0xf bound_ctrl:1
	s_nop 1
	v_mov_b32_dpp v22, v19 row_bcast:15 row_mask:0xa bank_mask:0xf bound_ctrl:1
	v_add_f32_e32 v19, v19, v22
	v_mov_b32_e32 v22, v107
	s_nop 1
	v_mov_b32_dpp v22, v19 row_bcast:31 row_mask:0xc bank_mask:0xf bound_ctrl:1
	v_add_f32_e32 v19, v19, v22
	v_sub_f32_e32 v18, v19, v18
	v_fma_f32 v18, v16, -v139, v18
	v_fma_f32 v19, v17, -v139, v18
	ds_write_b64 v20, v[18:19]
	ds_write_b64 v21, v[16:17]
	s_branch .LBB0_317

; #define LAS __attribute__((address_space(3)))
; __device__ __forceinline__ unsigned pk2e(float lo, float hi) { typedef __bf16 b2 __attribute__((ext_vector_type(2))); b2 v; v.x = (__bf16)lo; v.y = (__bf16)hi; return __builtin_bit_cast(unsigned, v); }
; __device__ __forceinline__ float ex2(float x) { return __builtin_amdgcn_exp2f(x); }
;     __device__ __forceinline__ void operator()(const f32x4 (&acc)[2][2][4][2], const Unit& u, int wr, int wc, int fr, int fq, LAS unsigned char* hb) const {
;     ...
; #pragma unroll
;         for (int n = 0; n < 2; ++n) { asm volatile("" ::: "memory");
;             const int c4 = ch + 4 * n;
;             const f32x4 w0 = *(const f32x4*)(cw + 0 * DFF + c4), w1 = *(const f32x4*)(cw + 1 * DFF + c4), w2 = *(const f32x4*)(cw + 2 * DFF + c4), bs = *(const f32x4*)(cb + c4);
; #pragma unroll
;             for (int ai = 0; ai < 2; ++ai)
; #pragma unroll
;                 for (int m = 0; m < 4; ++m) { const int q = 8 * ai + 4 * wr + m, prev = q > 0 ? q - 1 : 0; const int lr = ai * HALF + wr * 64 + m * 16 + fr, R = R0 + lr;
;                     const int Rc = R < 0 ? 0 : R; const int b = Rc / LL, p = Rc - b * LL;
;                     const LAS unsigned char* hp = hb + (prev * H * NCH + chl + 4 * n) * 4;
;                     const f32x4 h1 = *(const LAS f32x4*)(hp + hr1 * NCH * 4), h2 = *(const LAS f32x4*)(hp + hr2 * NCH * 4);
;                     const f32x4 gv = acc[ai][0][m][n], uv = acc[ai][1][m][n];
;                     float o[4];
; #pragma unroll
;                     for (int j = 0; j < 4; ++j) { const float g = gv[j];
;                         float g1 = dpp_row_shr<1>(h1[j], g), g2 = dpp_row_shr<2>(h2[j], g);
;                         g1 = p >= 1 ? g1 : 0.f; g2 = p >= 2 ? g2 : 0.f;
;                         const float v = bs[j] + w2[j] * g + w1[j] * g1 + w0[j] * g2;
;                         const float a = v + 0.044715f * v * v * v;
;                         const float ge = v * __builtin_amdgcn_rcpf(1.f + ex2(-2.f * 0.7978845608028654f * 1.4426950408889634f * a));
;                         o[j] = ge * uv[j]; }
;                     if (lr >= H && R < TT && p >= NMETA) { u32x2 w; w.x = pk2e(o[0], o[1]); w.y = pk2e(o[2], o[3]);
;                         *(u32x2*)(ACT + ((size_t)b * SEQ + p - NMETA) * DFF + c4) = w; } }
;         }
.LBB0_888:
	s_or_b64 exec, exec, s[6:7]
	v_readlane_b32 s72, v237, 30
	v_lshl_add_u32 v170, s40, 7, v116
	v_readlane_b32 s76, v237, 34
	v_readlane_b32 s77, v237, 35
	v_readlane_b32 s78, v237, 36
	v_readlane_b32 s79, v237, 37
	v_readlane_b32 s80, v237, 38
	v_readlane_b32 s81, v237, 39
	v_readlane_b32 s82, v237, 40
	v_readlane_b32 s83, v237, 41
	v_ashrrev_i32_e32 v171, 31, v170
	v_readlane_b32 s76, v237, 0
	s_waitcnt lgkmcnt(0)
	s_barrier
	v_lshlrev_b64 v[132:133], 2, v[170:171]
	v_readlane_b32 s86, v237, 44
	v_readlane_b32 s87, v237, 45
	v_readlane_b32 s77, v237, 1
	v_lshl_add_u64 v[176:177], s[18:19], 0, v[132:133]
	v_lshl_add_u64 v[172:173], s[86:87], 0, v[132:133]
	v_lshl_add_u64 v[178:179], s[76:77], 0, v[132:133]
	v_lshl_add_u64 v[174:175], s[16:17], 0, v[132:133]
	global_load_dwordx4 v[116:119], v[172:173], off
	global_load_dwordx4 v[120:123], v[174:175], off
	global_load_dwordx4 v[128:131], v[176:177], off
	global_load_dwordx4 v[132:135], v[178:179], off
	s_mul_i32 s21, s30, 0xfe
	s_add_i32 s21, s21, -2
	v_add_u32_e32 v190, s47, v144
	v_min_i32_e32 v145, 1, v144
	v_add_u32_e32 v189, s21, v190
	v_add_u32_e32 v191, 0xfffffc00, v188
	v_lshlrev_b32_e32 v187, 9, v145
	v_max_i32_e32 v192, 0, v189
	v_add_u32_e32 v144, s51, v191
	v_mul_hi_u32 v193, v192, s64
	v_add_u32_e32 v145, v144, v187
	ds_read_b128 v[148:151], v144 offset:512
	ds_read_b128 v[144:147], v145
	v_lshrrev_b32_e32 v193, 11, v193
	v_mul_i32_i24_e32 v194, 0xffffeff0, v193
	v_add_u32_e32 v192, v194, v192
	v_cmp_lt_i32_e32 vcc, 1, v190
	v_cmp_lt_i32_e64 s[8:9], 15, v192
	v_cmp_gt_i32_e64 s[6:7], s65, v189
	s_and_b64 s[8:9], vcc, s[8:9]
	s_waitcnt lgkmcnt(0)
	v_mov_b32_dpp v148, v140 row_shr:1 row_mask:0xf bank_mask:0xf
	v_mov_b32_dpp v144, v140 row_shr:2 row_mask:0xf bank_mask:0xf
	v_mov_b32_dpp v149, v141 row_shr:1 row_mask:0xf bank_mask:0xf
	v_mov_b32_dpp v145, v141 row_shr:2 row_mask:0xf bank_mask:0xf
	v_mov_b32_dpp v150, v142 row_shr:1 row_mask:0xf bank_mask:0xf
	v_mov_b32_dpp v146, v142 row_shr:2 row_mask:0xf bank_mask:0xf
	v_mov_b32_dpp v151, v143 row_shr:1 row_mask:0xf bank_mask:0xf
	v_mov_b32_dpp v147, v143 row_shr:2 row_mask:0xf bank_mask:0xf
	s_and_b64 s[26:27], s[8:9], s[6:7]
	v_lshl_add_u32 v189, v193, 12, v192
	v_readlane_b32 s73, v237, 31
	v_readlane_b32 s74, v237, 32
	v_readlane_b32 s75, v237, 33
	v_readlane_b32 s84, v237, 42
	v_readlane_b32 s85, v237, 43
	v_readlane_b32 s78, v237, 2
	v_readlane_b32 s79, v237, 3
	v_readlane_b32 s80, v237, 4
	v_readlane_b32 s81, v237, 5
	v_readlane_b32 s82, v237, 6
	v_readlane_b32 s83, v237, 7
	s_and_saveexec_b64 s[6:7], s[26:27]
	s_cbranch_execz .LBB0_890
	s_waitcnt vmcnt(0)
	v_pk_fma_f32 v[140:141], v[140:141], v[128:129], v[132:133]
	v_pk_fma_f32 v[142:143], v[142:143], v[130:131], v[134:135]
	v_pk_fma_f32 v[140:141], v[120:121], v[148:149], v[140:141]
	v_pk_fma_f32 v[142:143], v[122:123], v[150:151], v[142:143]
	v_pk_fma_f32 v[140:141], v[116:117], v[144:145], v[140:141]
	v_pk_fma_f32 v[142:143], v[118:119], v[146:147], v[142:143]
	v_mul_f32_e32 v144, 0x3d372713, v141
	v_mul_f32_e32 v144, v141, v144
	v_mul_f32_e32 v145, 0x3d372713, v140
	v_fma_f32 v144, v141, v144, v141
	v_mul_f32_e32 v145, v140, v145
	v_mul_f32_e32 v144, 0xc0135761, v144
	v_fma_f32 v145, v140, v145, v140
	v_exp_f32_e32 v144, v144
	v_mul_f32_e32 v145, 0xc0135761, v145
	v_mul_f32_e32 v146, 0x3d372713, v143
	v_exp_f32_e32 v148, v145
	v_mul_f32_e32 v146, v143, v146
	v_mul_f32_e32 v147, 0x3d372713, v142
	v_fma_f32 v146, v143, v146, v143
	v_mul_f32_e32 v147, v142, v147
	v_mul_f32_e32 v146, 0xc0135761, v146
	v_fma_f32 v147, v142, v147, v142
	v_add_f32_e32 v144, 1.0, v144
	v_exp_f32_e32 v146, v146
	v_mul_f32_e32 v147, 0xc0135761, v147
	v_rcp_f32_e32 v145, v144
	v_add_f32_e32 v144, 1.0, v148
	v_exp_f32_e32 v148, v147
	v_add_f32_e32 v146, 1.0, v146
	v_rcp_f32_e32 v144, v144
	v_rcp_f32_e32 v147, v146
	v_add_f32_e32 v146, 1.0, v148
	v_rcp_f32_e32 v146, v146
	v_pk_mul_f32 v[140:141], v[140:141], v[144:145]
	v_pk_mul_f32 v[136:137], v[136:137], v[140:141]
	v_pk_mul_f32 v[140:141], v[142:143], v[146:147]
	v_pk_mul_f32 v[138:139], v[138:139], v[140:141]
	v_cvt_pk_bf16_f32 v196, v136, v137
	v_cvt_pk_bf16_f32 v197, v138, v139
.LBB0_890:
	s_or_b64 exec, exec, s[6:7]
	v_add_u32_e32 v144, 16, v190
	v_add_u32_e32 v145, s21, v144
	v_max_i32_e32 v146, 0, v145
	v_add_u32_e32 v136, s52, v191
	v_mul_hi_u32 v147, v146, s64
	v_add_u32_e32 v137, v136, v187
	ds_read_b128 v[140:143], v136 offset:512
	ds_read_b128 v[136:139], v137
	v_lshrrev_b32_e32 v147, 11, v147
	v_mul_i32_i24_e32 v148, 0xffffeff0, v147
	v_add_u32_e32 v146, v148, v146
	v_cmp_lt_i32_e32 vcc, 1, v144
	v_cmp_lt_i32_e64 s[8:9], 15, v146
	v_cmp_gt_i32_e64 s[6:7], s65, v145
	s_and_b64 s[8:9], vcc, s[8:9]
	s_waitcnt lgkmcnt(0)
	v_mov_b32_dpp v140, v124 row_shr:1 row_mask:0xf bank_mask:0xf
	v_mov_b32_dpp v136, v124 row_shr:2 row_mask:0xf bank_mask:0xf
	v_mov_b32_dpp v141, v125 row_shr:1 row_mask:0xf bank_mask:0xf
	v_mov_b32_dpp v137, v125 row_shr:2 row_mask:0xf bank_mask:0xf
	v_mov_b32_dpp v142, v126 row_shr:1 row_mask:0xf bank_mask:0xf
	v_mov_b32_dpp v138, v126 row_shr:2 row_mask:0xf bank_mask:0xf
	v_mov_b32_dpp v143, v127 row_shr:1 row_mask:0xf bank_mask:0xf
	v_mov_b32_dpp v139, v127 row_shr:2 row_mask:0xf bank_mask:0xf
	s_and_b64 s[28:29], s[8:9], s[6:7]
	v_lshl_add_u32 v144, v147, 12, v146
	s_and_saveexec_b64 s[6:7], s[28:29]
	s_cbranch_execz .LBB0_892
	s_waitcnt vmcnt(0)
	v_pk_fma_f32 v[124:125], v[124:125], v[128:129], v[132:133]
	v_pk_fma_f32 v[126:127], v[126:127], v[130:131], v[134:135]
	v_pk_fma_f32 v[124:125], v[120:121], v[140:141], v[124:125]
	v_pk_fma_f32 v[126:127], v[122:123], v[142:143], v[126:127]
	v_pk_fma_f32 v[124:125], v[116:117], v[136:137], v[124:125]
	v_pk_fma_f32 v[126:127], v[118:119], v[138:139], v[126:127]
	v_mul_f32_e32 v136, 0x3d372713, v125
	v_mul_f32_e32 v136, v125, v136
	v_mul_f32_e32 v137, 0x3d372713, v124
	v_fma_f32 v136, v125, v136, v125
	v_mul_f32_e32 v137, v124, v137
	v_mul_f32_e32 v136, 0xc0135761, v136
	v_fma_f32 v137, v124, v137, v124
	v_exp_f32_e32 v136, v136
	v_mul_f32_e32 v137, 0xc0135761, v137
	v_mul_f32_e32 v138, 0x3d372713, v127
	v_exp_f32_e32 v140, v137
	v_mul_f32_e32 v138, v127, v138
	v_mul_f32_e32 v139, 0x3d372713, v126
	v_fma_f32 v138, v127, v138, v127
	v_mul_f32_e32 v139, v126, v139
	v_mul_f32_e32 v138, 0xc0135761, v138
	v_fma_f32 v139, v126, v139, v126
	v_add_f32_e32 v136, 1.0, v136
	v_exp_f32_e32 v138, v138
	v_mul_f32_e32 v139, 0xc0135761, v139
	v_rcp_f32_e32 v137, v136
	v_add_f32_e32 v136, 1.0, v140
	v_exp_f32_e32 v140, v139
	v_add_f32_e32 v138, 1.0, v138
	v_rcp_f32_e32 v136, v136
	v_rcp_f32_e32 v139, v138
	v_add_f32_e32 v138, 1.0, v140
	v_rcp_f32_e32 v138, v138
	v_pk_mul_f32 v[124:125], v[124:125], v[136:137]
	v_pk_mul_f32 v[112:113], v[112:113], v[124:125]
	v_pk_mul_f32 v[124:125], v[126:127], v[138:139]
	v_pk_mul_f32 v[114:115], v[114:115], v[124:125]
	v_cvt_pk_bf16_f32 v200, v112, v113
	v_cvt_pk_bf16_f32 v201, v114, v115
; #define LAS __attribute__((address_space(3)))
; __device__ __forceinline__ unsigned pk2e(float lo, float hi) { typedef __bf16 b2 __attribute__((ext_vector_type(2))); b2 v; v.x = (__bf16)lo; v.y = (__bf16)hi; return __builtin_bit_cast(unsigned, v); }
; __device__ __forceinline__ float ex2(float x) { return __builtin_amdgcn_exp2f(x); }
;     __device__ __forceinline__ void operator()(const f32x4 (&acc)[2][2][4][2], const Unit& u, int wr, int wc, int fr, int fq, LAS unsigned char* hb) const {
;     ...
; #pragma unroll
;         for (int n = 0; n < 2; ++n) { asm volatile("" ::: "memory");
;             const int c4 = ch + 4 * n;
;             const f32x4 w0 = *(const f32x4*)(cw + 0 * DFF + c4), w1 = *(const f32x4*)(cw + 1 * DFF + c4), w2 = *(const f32x4*)(cw + 2 * DFF + c4), bs = *(const f32x4*)(cb + c4);
; #pragma unroll
;             for (int ai = 0; ai < 2; ++ai)
; #pragma unroll
;                 for (int m = 0; m < 4; ++m) { const int q = 8 * ai + 4 * wr + m, prev = q > 0 ? q - 1 : 0; const int lr = ai * HALF + wr * 64 + m * 16 + fr, R = R0 + lr;
;                     const int Rc = R < 0 ? 0 : R; const int b = Rc / LL, p = Rc - b * LL;
;                     const LAS unsigned char* hp = hb + (prev * H * NCH + chl + 4 * n) * 4;
;                     const f32x4 h1 = *(const LAS f32x4*)(hp + hr1 * NCH * 4), h2 = *(const LAS f32x4*)(hp + hr2 * NCH * 4);
;                     const f32x4 gv = acc[ai][0][m][n], uv = acc[ai][1][m][n];
;                     float o[4];
; #pragma unroll
;                     for (int j = 0; j < 4; ++j) { const float g = gv[j];
;                         float g1 = dpp_row_shr<1>(h1[j], g), g2 = dpp_row_shr<2>(h2[j], g);
;                         g1 = p >= 1 ? g1 : 0.f; g2 = p >= 2 ? g2 : 0.f;
;                         const float v = bs[j] + w2[j] * g + w1[j] * g1 + w0[j] * g2;
;                         const float a = v + 0.044715f * v * v * v;
;                         const float ge = v * __builtin_amdgcn_rcpf(1.f + ex2(-2.f * 0.7978845608028654f * 1.4426950408889634f * a));
;                         o[j] = ge * uv[j]; }
;                     if (lr >= H && R < TT && p >= NMETA) { u32x2 w; w.x = pk2e(o[0], o[1]); w.y = pk2e(o[2], o[3]);
;                         *(u32x2*)(ACT + ((size_t)b * SEQ + p - NMETA) * DFF + c4) = w; } }
;         }
.LBB0_892:
	s_or_b64 exec, exec, s[6:7]
	v_add_u32_e32 v136, 32, v190
	v_add_u32_e32 v137, s21, v136
	v_max_i32_e32 v138, 0, v137
	v_add_u32_e32 v112, s53, v191
	v_mul_hi_u32 v139, v138, s64
	v_add_u32_e32 v113, v112, v187
	ds_read_b128 v[124:127], v112 offset:512
	ds_read_b128 v[112:115], v113
	v_lshrrev_b32_e32 v139, 11, v139
	v_mul_i32_i24_e32 v140, 0xffffeff0, v139
	v_add_u32_e32 v138, v140, v138
	v_cmp_lt_i32_e32 vcc, 1, v136
	v_cmp_lt_i32_e64 s[8:9], 15, v138
	v_cmp_gt_i32_e64 s[6:7], s65, v137
	s_and_b64 s[8:9], vcc, s[8:9]
	s_waitcnt lgkmcnt(0)
	v_mov_b32_dpp v124, v108 row_shr:1 row_mask:0xf bank_mask:0xf
	v_mov_b32_dpp v112, v108 row_shr:2 row_mask:0xf bank_mask:0xf
	v_mov_b32_dpp v125, v109 row_shr:1 row_mask:0xf bank_mask:0xf
	v_mov_b32_dpp v113, v109 row_shr:2 row_mask:0xf bank_mask:0xf
	v_mov_b32_dpp v126, v110 row_shr:1 row_mask:0xf bank_mask:0xf
	v_mov_b32_dpp v114, v110 row_shr:2 row_mask:0xf bank_mask:0xf
	v_mov_b32_dpp v127, v111 row_shr:1 row_mask:0xf bank_mask:0xf
	v_mov_b32_dpp v115, v111 row_shr:2 row_mask:0xf bank_mask:0xf
	s_and_b64 s[30:31], s[8:9], s[6:7]
	v_lshl_add_u32 v136, v139, 12, v138
	s_and_saveexec_b64 s[6:7], s[30:31]
	s_cbranch_execz .LBB0_894
	s_waitcnt vmcnt(0)
	v_pk_fma_f32 v[108:109], v[108:109], v[128:129], v[132:133]
	v_pk_fma_f32 v[110:111], v[110:111], v[130:131], v[134:135]
	v_pk_fma_f32 v[108:109], v[120:121], v[124:125], v[108:109]
	v_pk_fma_f32 v[110:111], v[122:123], v[126:127], v[110:111]
	v_pk_fma_f32 v[108:109], v[116:117], v[112:113], v[108:109]
	v_pk_fma_f32 v[110:111], v[118:119], v[114:115], v[110:111]
	v_mul_f32_e32 v112, 0x3d372713, v109
	v_mul_f32_e32 v112, v109, v112
	v_mul_f32_e32 v113, 0x3d372713, v108
	v_fma_f32 v112, v109, v112, v109
	v_mul_f32_e32 v113, v108, v113
	v_mul_f32_e32 v112, 0xc0135761, v112
	v_fma_f32 v113, v108, v113, v108
	v_exp_f32_e32 v112, v112
	v_mul_f32_e32 v113, 0xc0135761, v113
	v_mul_f32_e32 v114, 0x3d372713, v111
	v_exp_f32_e32 v124, v113
	v_mul_f32_e32 v114, v111, v114
	v_mul_f32_e32 v115, 0x3d372713, v110
	v_fma_f32 v114, v111, v114, v111
	v_mul_f32_e32 v115, v110, v115
	v_mul_f32_e32 v114, 0xc0135761, v114
	v_fma_f32 v115, v110, v115, v110
	v_add_f32_e32 v112, 1.0, v112
	v_exp_f32_e32 v114, v114
	v_mul_f32_e32 v115, 0xc0135761, v115
	v_rcp_f32_e32 v113, v112
	v_add_f32_e32 v112, 1.0, v124
	v_exp_f32_e32 v124, v115
	v_add_f32_e32 v114, 1.0, v114
	v_rcp_f32_e32 v112, v112
	v_rcp_f32_e32 v115, v114
	v_add_f32_e32 v114, 1.0, v124
	v_rcp_f32_e32 v114, v114
	v_pk_mul_f32 v[108:109], v[108:109], v[112:113]
	v_pk_mul_f32 v[104:105], v[104:105], v[108:109]
	v_pk_mul_f32 v[108:109], v[110:111], v[114:115]
	v_pk_mul_f32 v[106:107], v[106:107], v[108:109]
	v_cvt_pk_bf16_f32 v204, v104, v105
	v_cvt_pk_bf16_f32 v205, v106, v107
.LBB0_894:
	s_or_b64 exec, exec, s[6:7]
	v_add_u32_e32 v112, 48, v190
	v_add_u32_e32 v113, s21, v112
	v_max_i32_e32 v114, 0, v113
	v_add_u32_e32 v104, s54, v191
	v_mul_hi_u32 v115, v114, s64
	v_add_u32_e32 v105, v104, v187
	ds_read_b128 v[108:111], v104 offset:512
	ds_read_b128 v[104:107], v105
	v_lshrrev_b32_e32 v115, 11, v115
	v_mul_i32_i24_e32 v124, 0xffffeff0, v115
	v_add_u32_e32 v114, v124, v114
	v_cmp_lt_i32_e32 vcc, 1, v112
	v_cmp_lt_i32_e64 s[8:9], 15, v114
	v_cmp_gt_i32_e64 s[6:7], s65, v113
	s_and_b64 s[8:9], vcc, s[8:9]
	s_waitcnt lgkmcnt(0)
	v_mov_b32_dpp v108, v100 row_shr:1 row_mask:0xf bank_mask:0xf
	v_mov_b32_dpp v104, v100 row_shr:2 row_mask:0xf bank_mask:0xf
	v_mov_b32_dpp v109, v101 row_shr:1 row_mask:0xf bank_mask:0xf
	v_mov_b32_dpp v105, v101 row_shr:2 row_mask:0xf bank_mask:0xf
	v_mov_b32_dpp v110, v102 row_shr:1 row_mask:0xf bank_mask:0xf
	v_mov_b32_dpp v106, v102 row_shr:2 row_mask:0xf bank_mask:0xf
	v_mov_b32_dpp v111, v103 row_shr:1 row_mask:0xf bank_mask:0xf
	v_mov_b32_dpp v107, v103 row_shr:2 row_mask:0xf bank_mask:0xf
	s_and_b64 s[34:35], s[8:9], s[6:7]
	v_lshl_add_u32 v112, v115, 12, v114
	s_and_saveexec_b64 s[6:7], s[34:35]
	s_cbranch_execz .LBB0_896
	s_waitcnt vmcnt(0)
	v_pk_fma_f32 v[100:101], v[100:101], v[128:129], v[132:133]
	v_pk_fma_f32 v[102:103], v[102:103], v[130:131], v[134:135]
	v_pk_fma_f32 v[100:101], v[120:121], v[108:109], v[100:101]
	v_pk_fma_f32 v[102:103], v[122:123], v[110:111], v[102:103]
	v_pk_fma_f32 v[100:101], v[116:117], v[104:105], v[100:101]
	v_pk_fma_f32 v[102:103], v[118:119], v[106:107], v[102:103]
	v_mul_f32_e32 v104, 0x3d372713, v101
	v_mul_f32_e32 v104, v101, v104
	v_mul_f32_e32 v105, 0x3d372713, v100
	v_fma_f32 v104, v101, v104, v101
	v_mul_f32_e32 v105, v100, v105
	v_mul_f32_e32 v104, 0xc0135761, v104
	v_fma_f32 v105, v100, v105, v100
	v_exp_f32_e32 v104, v104
	v_mul_f32_e32 v105, 0xc0135761, v105
	v_mul_f32_e32 v106, 0x3d372713, v103
	v_exp_f32_e32 v108, v105
	v_mul_f32_e32 v106, v103, v106
	v_mul_f32_e32 v107, 0x3d372713, v102
	v_fma_f32 v106, v103, v106, v103
	v_mul_f32_e32 v107, v102, v107
	v_mul_f32_e32 v106, 0xc0135761, v106
	v_fma_f32 v107, v102, v107, v102
	v_add_f32_e32 v104, 1.0, v104
	v_exp_f32_e32 v106, v106
	v_mul_f32_e32 v107, 0xc0135761, v107
	v_rcp_f32_e32 v105, v104
	v_add_f32_e32 v104, 1.0, v108
	v_exp_f32_e32 v108, v107
	v_add_f32_e32 v106, 1.0, v106
	v_rcp_f32_e32 v104, v104
	v_rcp_f32_e32 v107, v106
	v_add_f32_e32 v106, 1.0, v108
	v_rcp_f32_e32 v106, v106
	v_pk_mul_f32 v[100:101], v[100:101], v[104:105]
	v_pk_mul_f32 v[96:97], v[96:97], v[100:101]
	v_pk_mul_f32 v[100:101], v[102:103], v[106:107]
	v_pk_mul_f32 v[98:99], v[98:99], v[100:101]
	v_cvt_pk_bf16_f32 v208, v96, v97
	v_cvt_pk_bf16_f32 v209, v98, v99
; #define LAS __attribute__((address_space(3)))
; __device__ __forceinline__ unsigned pk2e(float lo, float hi) { typedef __bf16 b2 __attribute__((ext_vector_type(2))); b2 v; v.x = (__bf16)lo; v.y = (__bf16)hi; return __builtin_bit_cast(unsigned, v); }
; __device__ __forceinline__ float ex2(float x) { return __builtin_amdgcn_exp2f(x); }
;     __device__ __forceinline__ void operator()(const f32x4 (&acc)[2][2][4][2], const Unit& u, int wr, int wc, int fr, int fq, LAS unsigned char* hb) const {
;     ...
; #pragma unroll
;         for (int n = 0; n < 2; ++n) { asm volatile("" ::: "memory");
;             const int c4 = ch + 4 * n;
;             const f32x4 w0 = *(const f32x4*)(cw + 0 * DFF + c4), w1 = *(const f32x4*)(cw + 1 * DFF + c4), w2 = *(const f32x4*)(cw + 2 * DFF + c4), bs = *(const f32x4*)(cb + c4);
; #pragma unroll
;             for (int ai = 0; ai < 2; ++ai)
; #pragma unroll
;                 for (int m = 0; m < 4; ++m) { const int q = 8 * ai + 4 * wr + m, prev = q > 0 ? q - 1 : 0; const int lr = ai * HALF + wr * 64 + m * 16 + fr, R = R0 + lr;
;                     const int Rc = R < 0 ? 0 : R; const int b = Rc / LL, p = Rc - b * LL;
;                     const LAS unsigned char* hp = hb + (prev * H * NCH + chl + 4 * n) * 4;
;                     const f32x4 h1 = *(const LAS f32x4*)(hp + hr1 * NCH * 4), h2 = *(const LAS f32x4*)(hp + hr2 * NCH * 4);
;                     const f32x4 gv = acc[ai][0][m][n], uv = acc[ai][1][m][n];
;                     float o[4];
; #pragma unroll
;                     for (int j = 0; j < 4; ++j) { const float g = gv[j];
;                         float g1 = dpp_row_shr<1>(h1[j], g), g2 = dpp_row_shr<2>(h2[j], g);
;                         g1 = p >= 1 ? g1 : 0.f; g2 = p >= 2 ? g2 : 0.f;
;                         const float v = bs[j] + w2[j] * g + w1[j] * g1 + w0[j] * g2;
;                         const float a = v + 0.044715f * v * v * v;
;                         const float ge = v * __builtin_amdgcn_rcpf(1.f + ex2(-2.f * 0.7978845608028654f * 1.4426950408889634f * a));
;                         o[j] = ge * uv[j]; }
;                     if (lr >= H && R < TT && p >= NMETA) { u32x2 w; w.x = pk2e(o[0], o[1]); w.y = pk2e(o[2], o[3]);
;                         *(u32x2*)(ACT + ((size_t)b * SEQ + p - NMETA) * DFF + c4) = w; } }
;         }
.LBB0_896:
	s_or_b64 exec, exec, s[6:7]
	v_add_u32_e32 v104, 0x80, v190
	v_add_u32_e32 v107, s21, v104
	v_max_i32_e32 v108, 0, v107
	v_mul_hi_u32 v109, v108, s64
	v_add_u32_e32 v105, s55, v188
	v_add_u32_e32 v106, v105, v187
	ds_read_b128 v[100:103], v105 offset:7680
	ds_read_b128 v[96:99], v106 offset:7168
	v_lshrrev_b32_e32 v109, 11, v109
	v_mul_i32_i24_e32 v110, 0xffffeff0, v109
	v_add_u32_e32 v108, v110, v108
	v_cmp_lt_i32_e32 vcc, 1, v104
	v_cmp_lt_i32_e64 s[8:9], 15, v108
	v_cmp_gt_i32_e64 s[6:7], s65, v107
	s_and_b64 s[8:9], vcc, s[8:9]
	s_waitcnt lgkmcnt(0)
	v_mov_b32_dpp v100, v92 row_shr:1 row_mask:0xf bank_mask:0xf
	v_mov_b32_dpp v96, v92 row_shr:2 row_mask:0xf bank_mask:0xf
	v_mov_b32_dpp v101, v93 row_shr:1 row_mask:0xf bank_mask:0xf
	v_mov_b32_dpp v97, v93 row_shr:2 row_mask:0xf bank_mask:0xf
	v_mov_b32_dpp v102, v94 row_shr:1 row_mask:0xf bank_mask:0xf
	v_mov_b32_dpp v98, v94 row_shr:2 row_mask:0xf bank_mask:0xf
	v_mov_b32_dpp v103, v95 row_shr:1 row_mask:0xf bank_mask:0xf
	v_mov_b32_dpp v99, v95 row_shr:2 row_mask:0xf bank_mask:0xf
	s_and_b64 s[36:37], s[8:9], s[6:7]
	v_lshl_add_u32 v104, v109, 12, v108
	s_and_saveexec_b64 s[6:7], s[36:37]
	s_cbranch_execz .LBB0_898
	s_waitcnt vmcnt(0)
	v_pk_fma_f32 v[92:93], v[92:93], v[128:129], v[132:133]
	v_pk_fma_f32 v[94:95], v[94:95], v[130:131], v[134:135]
	v_pk_fma_f32 v[92:93], v[120:121], v[100:101], v[92:93]
	v_pk_fma_f32 v[94:95], v[122:123], v[102:103], v[94:95]
	v_pk_fma_f32 v[92:93], v[116:117], v[96:97], v[92:93]
	v_pk_fma_f32 v[94:95], v[118:119], v[98:99], v[94:95]
	v_mul_f32_e32 v96, 0x3d372713, v93
	v_mul_f32_e32 v96, v93, v96
	v_mul_f32_e32 v97, 0x3d372713, v92
	v_fma_f32 v96, v93, v96, v93
	v_mul_f32_e32 v97, v92, v97
	v_mul_f32_e32 v96, 0xc0135761, v96
	v_fma_f32 v97, v92, v97, v92
	v_exp_f32_e32 v96, v96
	v_mul_f32_e32 v97, 0xc0135761, v97
	v_mul_f32_e32 v98, 0x3d372713, v95
	v_exp_f32_e32 v100, v97
	v_mul_f32_e32 v98, v95, v98
	v_mul_f32_e32 v99, 0x3d372713, v94
	v_fma_f32 v98, v95, v98, v95
	v_mul_f32_e32 v99, v94, v99
	v_mul_f32_e32 v98, 0xc0135761, v98
	v_fma_f32 v99, v94, v99, v94
	v_add_f32_e32 v96, 1.0, v96
	v_exp_f32_e32 v98, v98
	v_mul_f32_e32 v99, 0xc0135761, v99
	v_rcp_f32_e32 v97, v96
	v_add_f32_e32 v96, 1.0, v100
	v_exp_f32_e32 v100, v99
	v_add_f32_e32 v98, 1.0, v98
	v_rcp_f32_e32 v96, v96
	v_rcp_f32_e32 v99, v98
	v_add_f32_e32 v98, 1.0, v100
	v_rcp_f32_e32 v98, v98
	v_pk_mul_f32 v[92:93], v[92:93], v[96:97]
	v_pk_mul_f32 v[88:89], v[88:89], v[92:93]
	v_pk_mul_f32 v[92:93], v[94:95], v[98:99]
	v_pk_mul_f32 v[90:91], v[90:91], v[92:93]
	v_cvt_pk_bf16_f32 v212, v88, v89
	v_cvt_pk_bf16_f32 v213, v90, v91
.LBB0_898:
	s_or_b64 exec, exec, s[6:7]
	v_add_u32_e32 v96, 0x90, v190
	v_add_u32_e32 v99, s21, v96
	v_max_i32_e32 v100, 0, v99
	v_mul_hi_u32 v101, v100, s64
	v_add_u32_e32 v97, s56, v188
	v_add_u32_e32 v98, v97, v187
	ds_read_b128 v[92:95], v97 offset:8704
	ds_read_b128 v[88:91], v98 offset:8192
	v_lshrrev_b32_e32 v101, 11, v101
	v_mul_i32_i24_e32 v102, 0xffffeff0, v101
	v_add_u32_e32 v100, v102, v100
	v_cmp_lt_i32_e32 vcc, 1, v96
	v_cmp_lt_i32_e64 s[8:9], 15, v100
	v_cmp_gt_i32_e64 s[6:7], s65, v99
	s_and_b64 s[8:9], vcc, s[8:9]
	s_waitcnt lgkmcnt(0)
	v_mov_b32_dpp v92, v84 row_shr:1 row_mask:0xf bank_mask:0xf
	v_mov_b32_dpp v88, v84 row_shr:2 row_mask:0xf bank_mask:0xf
	v_mov_b32_dpp v93, v85 row_shr:1 row_mask:0xf bank_mask:0xf
	v_mov_b32_dpp v89, v85 row_shr:2 row_mask:0xf bank_mask:0xf
	v_mov_b32_dpp v94, v86 row_shr:1 row_mask:0xf bank_mask:0xf
	v_mov_b32_dpp v90, v86 row_shr:2 row_mask:0xf bank_mask:0xf
	v_mov_b32_dpp v95, v87 row_shr:1 row_mask:0xf bank_mask:0xf
	v_mov_b32_dpp v91, v87 row_shr:2 row_mask:0xf bank_mask:0xf
	s_and_b64 s[38:39], s[8:9], s[6:7]
	v_lshl_add_u32 v96, v101, 12, v100
	s_and_saveexec_b64 s[6:7], s[38:39]
	s_cbranch_execz .LBB0_900
	s_waitcnt vmcnt(0)
	v_pk_fma_f32 v[84:85], v[84:85], v[128:129], v[132:133]
	v_pk_fma_f32 v[86:87], v[86:87], v[130:131], v[134:135]
	v_pk_fma_f32 v[84:85], v[120:121], v[92:93], v[84:85]
	v_pk_fma_f32 v[86:87], v[122:123], v[94:95], v[86:87]
	v_pk_fma_f32 v[84:85], v[116:117], v[88:89], v[84:85]
	v_pk_fma_f32 v[86:87], v[118:119], v[90:91], v[86:87]
	v_mul_f32_e32 v88, 0x3d372713, v85
	v_mul_f32_e32 v88, v85, v88
	v_mul_f32_e32 v89, 0x3d372713, v84
	v_fma_f32 v88, v85, v88, v85
	v_mul_f32_e32 v89, v84, v89
	v_mul_f32_e32 v88, 0xc0135761, v88
	v_fma_f32 v89, v84, v89, v84
	v_exp_f32_e32 v88, v88
	v_mul_f32_e32 v89, 0xc0135761, v89
	v_mul_f32_e32 v90, 0x3d372713, v87
	v_exp_f32_e32 v92, v89
	v_mul_f32_e32 v90, v87, v90
	v_mul_f32_e32 v91, 0x3d372713, v86
	v_fma_f32 v90, v87, v90, v87
	v_mul_f32_e32 v91, v86, v91
	v_mul_f32_e32 v90, 0xc0135761, v90
	v_fma_f32 v91, v86, v91, v86
	v_add_f32_e32 v88, 1.0, v88
	v_exp_f32_e32 v90, v90
	v_mul_f32_e32 v91, 0xc0135761, v91
	v_rcp_f32_e32 v89, v88
	v_add_f32_e32 v88, 1.0, v92
	v_exp_f32_e32 v92, v91
	v_add_f32_e32 v90, 1.0, v90
	v_rcp_f32_e32 v88, v88
	v_rcp_f32_e32 v91, v90
	v_add_f32_e32 v90, 1.0, v92
	v_rcp_f32_e32 v90, v90
	v_pk_mul_f32 v[84:85], v[84:85], v[88:89]
	v_pk_mul_f32 v[80:81], v[80:81], v[84:85]
	v_pk_mul_f32 v[84:85], v[86:87], v[90:91]
	v_pk_mul_f32 v[82:83], v[82:83], v[84:85]
	v_cvt_pk_bf16_f32 v216, v80, v81
	v_cvt_pk_bf16_f32 v217, v82, v83
; #define LAS __attribute__((address_space(3)))
; __device__ __forceinline__ unsigned pk2e(float lo, float hi) { typedef __bf16 b2 __attribute__((ext_vector_type(2))); b2 v; v.x = (__bf16)lo; v.y = (__bf16)hi; return __builtin_bit_cast(unsigned, v); }
; __device__ __forceinline__ float ex2(float x) { return __builtin_amdgcn_exp2f(x); }
;     __device__ __forceinline__ void operator()(const f32x4 (&acc)[2][2][4][2], const Unit& u, int wr, int wc, int fr, int fq, LAS unsigned char* hb) const {
;     ...
; #pragma unroll
;         for (int n = 0; n < 2; ++n) { asm volatile("" ::: "memory");
;             const int c4 = ch + 4 * n;
;             const f32x4 w0 = *(const f32x4*)(cw + 0 * DFF + c4), w1 = *(const f32x4*)(cw + 1 * DFF + c4), w2 = *(const f32x4*)(cw + 2 * DFF + c4), bs = *(const f32x4*)(cb + c4);
; #pragma unroll
;             for (int ai = 0; ai < 2; ++ai)
; #pragma unroll
;                 for (int m = 0; m < 4; ++m) { const int q = 8 * ai + 4 * wr + m, prev = q > 0 ? q - 1 : 0; const int lr = ai * HALF + wr * 64 + m * 16 + fr, R = R0 + lr;
;                     const int Rc = R < 0 ? 0 : R; const int b = Rc / LL, p = Rc - b * LL;
;                     const LAS unsigned char* hp = hb + (prev * H * NCH + chl + 4 * n) * 4;
;                     const f32x4 h1 = *(const LAS f32x4*)(hp + hr1 * NCH * 4), h2 = *(const LAS f32x4*)(hp + hr2 * NCH * 4);
;                     const f32x4 gv = acc[ai][0][m][n], uv = acc[ai][1][m][n];
;                     float o[4];
; #pragma unroll
;                     for (int j = 0; j < 4; ++j) { const float g = gv[j];
;                         float g1 = dpp_row_shr<1>(h1[j], g), g2 = dpp_row_shr<2>(h2[j], g);
;                         g1 = p >= 1 ? g1 : 0.f; g2 = p >= 2 ? g2 : 0.f;
;                         const float v = bs[j] + w2[j] * g + w1[j] * g1 + w0[j] * g2;
;                         const float a = v + 0.044715f * v * v * v;
;                         const float ge = v * __builtin_amdgcn_rcpf(1.f + ex2(-2.f * 0.7978845608028654f * 1.4426950408889634f * a));
;                         o[j] = ge * uv[j]; }
;                     if (lr >= H && R < TT && p >= NMETA) { u32x2 w; w.x = pk2e(o[0], o[1]); w.y = pk2e(o[2], o[3]);
;                         *(u32x2*)(ACT + ((size_t)b * SEQ + p - NMETA) * DFF + c4) = w; } }
;         }
.LBB0_900:
	s_or_b64 exec, exec, s[6:7]
	v_add_u32_e32 v88, 0xa0, v190
	v_add_u32_e32 v89, s21, v88
	v_max_i32_e32 v90, 0, v89
	v_mul_hi_u32 v91, v90, s64
	v_add_u32_e32 v92, s57, v188
	v_add_u32_e32 v93, v92, v187
	ds_read_b128 v[84:87], v92 offset:9728
	ds_read_b128 v[80:83], v93 offset:9216
	v_lshrrev_b32_e32 v91, 11, v91
	v_mul_i32_i24_e32 v94, 0xffffeff0, v91
	v_add_u32_e32 v90, v94, v90
	v_cmp_lt_i32_e32 vcc, 1, v88
	v_cmp_lt_i32_e64 s[8:9], 15, v90
	v_cmp_gt_i32_e64 s[6:7], s65, v89
	s_and_b64 s[8:9], vcc, s[8:9]
	s_waitcnt lgkmcnt(0)
	v_mov_b32_dpp v84, v76 row_shr:1 row_mask:0xf bank_mask:0xf
	v_mov_b32_dpp v80, v76 row_shr:2 row_mask:0xf bank_mask:0xf
	v_mov_b32_dpp v85, v77 row_shr:1 row_mask:0xf bank_mask:0xf
	v_mov_b32_dpp v81, v77 row_shr:2 row_mask:0xf bank_mask:0xf
	v_mov_b32_dpp v86, v78 row_shr:1 row_mask:0xf bank_mask:0xf
	v_mov_b32_dpp v82, v78 row_shr:2 row_mask:0xf bank_mask:0xf
	v_mov_b32_dpp v87, v79 row_shr:1 row_mask:0xf bank_mask:0xf
	v_mov_b32_dpp v83, v79 row_shr:2 row_mask:0xf bank_mask:0xf
	s_and_b64 s[40:41], s[8:9], s[6:7]
	v_lshl_add_u32 v90, v91, 12, v90
	s_and_saveexec_b64 s[6:7], s[40:41]
	s_cbranch_execz .LBB0_902
	s_waitcnt vmcnt(0)
	v_pk_fma_f32 v[76:77], v[76:77], v[128:129], v[132:133]
	v_pk_fma_f32 v[78:79], v[78:79], v[130:131], v[134:135]
	v_pk_fma_f32 v[76:77], v[120:121], v[84:85], v[76:77]
	v_pk_fma_f32 v[78:79], v[122:123], v[86:87], v[78:79]
	v_pk_fma_f32 v[76:77], v[116:117], v[80:81], v[76:77]
	v_pk_fma_f32 v[78:79], v[118:119], v[82:83], v[78:79]
	v_mul_f32_e32 v80, 0x3d372713, v77
	v_mul_f32_e32 v80, v77, v80
	v_mul_f32_e32 v81, 0x3d372713, v76
	v_fma_f32 v80, v77, v80, v77
	v_mul_f32_e32 v81, v76, v81
	v_mul_f32_e32 v80, 0xc0135761, v80
	v_fma_f32 v81, v76, v81, v76
	v_exp_f32_e32 v80, v80
	v_mul_f32_e32 v81, 0xc0135761, v81
	v_mul_f32_e32 v82, 0x3d372713, v79
	v_exp_f32_e32 v84, v81
	v_mul_f32_e32 v82, v79, v82
	v_mul_f32_e32 v83, 0x3d372713, v78
	v_fma_f32 v82, v79, v82, v79
	v_mul_f32_e32 v83, v78, v83
	v_mul_f32_e32 v82, 0xc0135761, v82
	v_fma_f32 v83, v78, v83, v78
	v_add_f32_e32 v80, 1.0, v80
	v_exp_f32_e32 v82, v82
	v_mul_f32_e32 v83, 0xc0135761, v83
	v_rcp_f32_e32 v81, v80
	v_add_f32_e32 v80, 1.0, v84
	v_exp_f32_e32 v84, v83
	v_add_f32_e32 v82, 1.0, v82
	v_rcp_f32_e32 v80, v80
	v_rcp_f32_e32 v83, v82
	v_add_f32_e32 v82, 1.0, v84
	v_rcp_f32_e32 v82, v82
	v_pk_mul_f32 v[76:77], v[76:77], v[80:81]
	v_pk_mul_f32 v[72:73], v[72:73], v[76:77]
	v_pk_mul_f32 v[76:77], v[78:79], v[82:83]
	v_pk_mul_f32 v[74:75], v[74:75], v[76:77]
	v_cvt_pk_bf16_f32 v228, v72, v73
	v_cvt_pk_bf16_f32 v229, v74, v75
.LBB0_902:
	s_or_b64 exec, exec, s[6:7]
	v_add_u32_e32 v80, 0xb0, v190
	v_add_u32_e32 v81, s21, v80
	v_max_i32_e32 v82, 0, v81
	v_mul_hi_u32 v83, v82, s64
	v_add_u32_e32 v94, s58, v188
	v_add_u32_e32 v95, v94, v187
	ds_read_b128 v[76:79], v94 offset:10752
	ds_read_b128 v[72:75], v95 offset:10240
	v_lshrrev_b32_e32 v83, 11, v83
	v_mul_i32_i24_e32 v84, 0xffffeff0, v83
	v_add_u32_e32 v82, v84, v82
	v_cmp_lt_i32_e32 vcc, 1, v80
	v_cmp_lt_i32_e64 s[8:9], 15, v82
	v_cmp_gt_i32_e64 s[6:7], s65, v81
	s_and_b64 s[8:9], vcc, s[8:9]
	s_waitcnt lgkmcnt(0)
	v_mov_b32_dpp v76, v68 row_shr:1 row_mask:0xf bank_mask:0xf
	v_mov_b32_dpp v72, v68 row_shr:2 row_mask:0xf bank_mask:0xf
	v_mov_b32_dpp v77, v69 row_shr:1 row_mask:0xf bank_mask:0xf
	v_mov_b32_dpp v73, v69 row_shr:2 row_mask:0xf bank_mask:0xf
	v_mov_b32_dpp v78, v70 row_shr:1 row_mask:0xf bank_mask:0xf
	v_mov_b32_dpp v74, v70 row_shr:2 row_mask:0xf bank_mask:0xf
	v_mov_b32_dpp v79, v71 row_shr:1 row_mask:0xf bank_mask:0xf
	v_mov_b32_dpp v75, v71 row_shr:2 row_mask:0xf bank_mask:0xf
	s_and_b64 s[6:7], s[8:9], s[6:7]
	v_lshl_add_u32 v91, v83, 12, v82
	s_and_saveexec_b64 s[8:9], s[6:7]
	s_cbranch_execz .LBB0_904
	s_waitcnt vmcnt(0)
	v_pk_fma_f32 v[68:69], v[68:69], v[128:129], v[132:133]
	v_pk_fma_f32 v[70:71], v[70:71], v[130:131], v[134:135]
	v_pk_fma_f32 v[68:69], v[120:121], v[76:77], v[68:69]
	v_pk_fma_f32 v[70:71], v[122:123], v[78:79], v[70:71]
	v_pk_fma_f32 v[68:69], v[116:117], v[72:73], v[68:69]
	v_pk_fma_f32 v[70:71], v[118:119], v[74:75], v[70:71]
	v_mul_f32_e32 v72, 0x3d372713, v69
	v_mul_f32_e32 v72, v69, v72
	v_mul_f32_e32 v73, 0x3d372713, v68
	v_fma_f32 v72, v69, v72, v69
	v_mul_f32_e32 v73, v68, v73
	v_mul_f32_e32 v72, 0xc0135761, v72
	v_fma_f32 v73, v68, v73, v68
	v_exp_f32_e32 v72, v72
	v_mul_f32_e32 v73, 0xc0135761, v73
	v_mul_f32_e32 v74, 0x3d372713, v71
	v_exp_f32_e32 v76, v73
	v_mul_f32_e32 v74, v71, v74
	v_mul_f32_e32 v75, 0x3d372713, v70
	v_fma_f32 v74, v71, v74, v71
	v_mul_f32_e32 v75, v70, v75
	v_mul_f32_e32 v74, 0xc0135761, v74
	v_fma_f32 v75, v70, v75, v70
	v_add_f32_e32 v72, 1.0, v72
	v_exp_f32_e32 v74, v74
	v_mul_f32_e32 v75, 0xc0135761, v75
	v_rcp_f32_e32 v73, v72
	v_add_f32_e32 v72, 1.0, v76
	v_exp_f32_e32 v76, v75
	v_add_f32_e32 v74, 1.0, v74
	v_rcp_f32_e32 v72, v72
	v_rcp_f32_e32 v75, v74
	v_add_f32_e32 v74, 1.0, v76
	v_rcp_f32_e32 v74, v74
	v_pk_mul_f32 v[68:69], v[68:69], v[72:73]
	v_pk_mul_f32 v[60:61], v[60:61], v[68:69]
	v_pk_mul_f32 v[68:69], v[70:71], v[74:75]
	v_pk_mul_f32 v[62:63], v[62:63], v[68:69]
	v_cvt_pk_bf16_f32 v232, v60, v61
	v_cvt_pk_bf16_f32 v233, v62, v63
; #define LAS __attribute__((address_space(3)))
; __device__ __forceinline__ unsigned pk2e(float lo, float hi) { typedef __bf16 b2 __attribute__((ext_vector_type(2))); b2 v; v.x = (__bf16)lo; v.y = (__bf16)hi; return __builtin_bit_cast(unsigned, v); }
; __device__ __forceinline__ float ex2(float x) { return __builtin_amdgcn_exp2f(x); }
;     __device__ __forceinline__ void operator()(const f32x4 (&acc)[2][2][4][2], const Unit& u, int wr, int wc, int fr, int fq, LAS unsigned char* hb) const {
;     ...
; #pragma unroll
;         for (int n = 0; n < 2; ++n) { asm volatile("" ::: "memory");
;             const int c4 = ch + 4 * n;
;             const f32x4 w0 = *(const f32x4*)(cw + 0 * DFF + c4), w1 = *(const f32x4*)(cw + 1 * DFF + c4), w2 = *(const f32x4*)(cw + 2 * DFF + c4), bs = *(const f32x4*)(cb + c4);
; #pragma unroll
;             for (int ai = 0; ai < 2; ++ai)
; #pragma unroll
;                 for (int m = 0; m < 4; ++m) { const int q = 8 * ai + 4 * wr + m, prev = q > 0 ? q - 1 : 0; const int lr = ai * HALF + wr * 64 + m * 16 + fr, R = R0 + lr;
;                     const int Rc = R < 0 ? 0 : R; const int b = Rc / LL, p = Rc - b * LL;
;                     const LAS unsigned char* hp = hb + (prev * H * NCH + chl + 4 * n) * 4;
;                     const f32x4 h1 = *(const LAS f32x4*)(hp + hr1 * NCH * 4), h2 = *(const LAS f32x4*)(hp + hr2 * NCH * 4);
;                     const f32x4 gv = acc[ai][0][m][n], uv = acc[ai][1][m][n];
;                     float o[4];
; #pragma unroll
;                     for (int j = 0; j < 4; ++j) { const float g = gv[j];
;                         float g1 = dpp_row_shr<1>(h1[j], g), g2 = dpp_row_shr<2>(h2[j], g);
;                         g1 = p >= 1 ? g1 : 0.f; g2 = p >= 2 ? g2 : 0.f;
;                         const float v = bs[j] + w2[j] * g + w1[j] * g1 + w0[j] * g2;
;                         const float a = v + 0.044715f * v * v * v;
;                         const float ge = v * __builtin_amdgcn_rcpf(1.f + ex2(-2.f * 0.7978845608028654f * 1.4426950408889634f * a));
;                         o[j] = ge * uv[j]; }
;                     if (lr >= H && R < TT && p >= NMETA) { u32x2 w; w.x = pk2e(o[0], o[1]); w.y = pk2e(o[2], o[3]);
;                         *(u32x2*)(ACT + ((size_t)b * SEQ + p - NMETA) * DFF + c4) = w; } }
;         }
.LBB0_904:
	s_or_b64 exec, exec, s[8:9]
	global_load_dwordx4 v[60:63], v[172:173], off offset:16
	global_load_dwordx4 v[68:71], v[174:175], off offset:16
	global_load_dwordx4 v[72:75], v[176:177], off offset:16
	global_load_dwordx4 v[76:79], v[178:179], off offset:16
	v_add_u32_e32 v99, 0xfffffc10, v188
	v_add_u32_e32 v80, s51, v99
	v_add_u32_e32 v81, v80, v187
	ds_read_b128 v[84:87], v80 offset:512
	ds_read_b128 v[80:83], v81
	v_add_u32_e32 v88, 4, v170
	v_ashrrev_i32_e32 v89, 31, v88
	s_waitcnt lgkmcnt(0)
	v_mov_b32_dpp v84, v64 row_shr:1 row_mask:0xf bank_mask:0xf
	v_mov_b32_dpp v80, v64 row_shr:2 row_mask:0xf bank_mask:0xf
	v_mov_b32_dpp v85, v65 row_shr:1 row_mask:0xf bank_mask:0xf
	v_mov_b32_dpp v81, v65 row_shr:2 row_mask:0xf bank_mask:0xf
	v_mov_b32_dpp v86, v66 row_shr:1 row_mask:0xf bank_mask:0xf
	v_mov_b32_dpp v82, v66 row_shr:2 row_mask:0xf bank_mask:0xf
	v_mov_b32_dpp v87, v67 row_shr:1 row_mask:0xf bank_mask:0xf
	v_mov_b32_dpp v83, v67 row_shr:2 row_mask:0xf bank_mask:0xf
	s_and_saveexec_b64 s[8:9], s[26:27]
	s_cbranch_execz .LBB0_906
	s_waitcnt vmcnt(0)
	v_pk_fma_f32 v[64:65], v[64:65], v[72:73], v[76:77]
	v_pk_fma_f32 v[66:67], v[66:67], v[74:75], v[78:79]
	v_pk_fma_f32 v[64:65], v[68:69], v[84:85], v[64:65]
	v_pk_fma_f32 v[66:67], v[70:71], v[86:87], v[66:67]
	v_pk_fma_f32 v[64:65], v[60:61], v[80:81], v[64:65]
	v_pk_fma_f32 v[66:67], v[62:63], v[82:83], v[66:67]
	v_mul_f32_e32 v80, 0x3d372713, v65
	v_mul_f32_e32 v80, v65, v80
	v_mul_f32_e32 v81, 0x3d372713, v64
	v_fma_f32 v80, v65, v80, v65
	v_mul_f32_e32 v81, v64, v81
	v_mul_f32_e32 v80, 0xc0135761, v80
	v_fma_f32 v81, v64, v81, v64
	v_exp_f32_e32 v80, v80
	v_mul_f32_e32 v81, 0xc0135761, v81
	v_mul_f32_e32 v82, 0x3d372713, v67
	v_exp_f32_e32 v84, v81
	v_mul_f32_e32 v82, v67, v82
	v_mul_f32_e32 v83, 0x3d372713, v66
	v_fma_f32 v82, v67, v82, v67
	v_mul_f32_e32 v83, v66, v83
	v_mul_f32_e32 v82, 0xc0135761, v82
	v_fma_f32 v83, v66, v83, v66
	v_add_f32_e32 v80, 1.0, v80
	v_exp_f32_e32 v82, v82
	v_mul_f32_e32 v83, 0xc0135761, v83
	v_rcp_f32_e32 v81, v80
	v_add_f32_e32 v80, 1.0, v84
	v_exp_f32_e32 v84, v83
	v_add_f32_e32 v82, 1.0, v82
	v_rcp_f32_e32 v80, v80
	v_rcp_f32_e32 v83, v82
	v_add_f32_e32 v82, 1.0, v84
	v_rcp_f32_e32 v82, v82
	v_pk_mul_f32 v[64:65], v[64:65], v[80:81]
	v_readlane_b32 s12, v237, 50
	v_pk_mul_f32 v[56:57], v[56:57], v[64:65]
	v_pk_mul_f32 v[64:65], v[66:67], v[82:83]
	v_readlane_b32 s13, v237, 51
	v_pk_mul_f32 v[58:59], v[58:59], v[64:65]
	v_cvt_pk_bf16_f32 v198, v56, v57
	v_cvt_pk_bf16_f32 v199, v58, v59
	v_mov_b64_e32 v[58:59], s[12:13]
	v_mad_u64_u32 v[58:59], s[26:27], v189, s66, v[58:59]
	v_lshl_add_u64 v[58:59], v[88:89], 1, v[58:59]
	v_add_co_u32_e32 v58, vcc, 0xfffea000, v58
	s_nop 1
	v_addc_co_u32_e32 v59, vcc, -1, v59, vcc
	global_store_dwordx4 v[58:59], v[196:199], off offset:-8
.LBB0_906:
	s_or_b64 exec, exec, s[8:9]
	v_add_u32_e32 v56, s52, v99
	ds_read_b128 v[64:67], v56 offset:512
	v_add_u32_e32 v56, v56, v187
	ds_read_b128 v[56:59], v56
	s_waitcnt lgkmcnt(0)
	v_mov_b32_dpp v64, v52 row_shr:1 row_mask:0xf bank_mask:0xf
	v_mov_b32_dpp v65, v53 row_shr:1 row_mask:0xf bank_mask:0xf
	v_mov_b32_dpp v56, v52 row_shr:2 row_mask:0xf bank_mask:0xf
	v_mov_b32_dpp v57, v53 row_shr:2 row_mask:0xf bank_mask:0xf
	v_mov_b32_dpp v66, v54 row_shr:1 row_mask:0xf bank_mask:0xf
	v_mov_b32_dpp v58, v54 row_shr:2 row_mask:0xf bank_mask:0xf
	v_mov_b32_dpp v67, v55 row_shr:1 row_mask:0xf bank_mask:0xf
	v_mov_b32_dpp v59, v55 row_shr:2 row_mask:0xf bank_mask:0xf
	s_and_saveexec_b64 s[8:9], s[28:29]
	s_cbranch_execz .LBB0_908
	s_waitcnt vmcnt(0)
	v_pk_fma_f32 v[52:53], v[52:53], v[72:73], v[76:77]
	v_pk_fma_f32 v[54:55], v[54:55], v[74:75], v[78:79]
	v_pk_fma_f32 v[52:53], v[68:69], v[64:65], v[52:53]
	v_pk_fma_f32 v[54:55], v[70:71], v[66:67], v[54:55]
	v_pk_fma_f32 v[52:53], v[60:61], v[56:57], v[52:53]
	v_pk_fma_f32 v[54:55], v[62:63], v[58:59], v[54:55]
	v_mul_f32_e32 v56, 0x3d372713, v53
	v_mul_f32_e32 v56, v53, v56
	v_mul_f32_e32 v57, 0x3d372713, v52
	v_fma_f32 v56, v53, v56, v53
	v_mul_f32_e32 v57, v52, v57
	v_mul_f32_e32 v56, 0xc0135761, v56
	v_fma_f32 v57, v52, v57, v52
	v_exp_f32_e32 v56, v56
	v_mul_f32_e32 v57, 0xc0135761, v57
	v_mul_f32_e32 v58, 0x3d372713, v55
	v_exp_f32_e32 v64, v57
	v_mul_f32_e32 v58, v55, v58
	v_mul_f32_e32 v59, 0x3d372713, v54
	v_fma_f32 v58, v55, v58, v55
	v_mul_f32_e32 v59, v54, v59
	v_mul_f32_e32 v58, 0xc0135761, v58
	v_fma_f32 v59, v54, v59, v54
	v_add_f32_e32 v56, 1.0, v56
	v_exp_f32_e32 v58, v58
	v_mul_f32_e32 v59, 0xc0135761, v59
	v_rcp_f32_e32 v57, v56
	v_add_f32_e32 v56, 1.0, v64
	v_exp_f32_e32 v64, v59
	v_add_f32_e32 v58, 1.0, v58
	v_rcp_f32_e32 v56, v56
	v_rcp_f32_e32 v59, v58
	v_add_f32_e32 v58, 1.0, v64
	v_rcp_f32_e32 v58, v58
	v_pk_mul_f32 v[52:53], v[52:53], v[56:57]
	v_readlane_b32 s12, v237, 50
	v_pk_mul_f32 v[48:49], v[48:49], v[52:53]
	v_pk_mul_f32 v[52:53], v[54:55], v[58:59]
	v_readlane_b32 s13, v237, 51
	v_pk_mul_f32 v[50:51], v[50:51], v[52:53]
	v_cvt_pk_bf16_f32 v202, v48, v49
	v_cvt_pk_bf16_f32 v203, v50, v51
	v_mov_b64_e32 v[50:51], s[12:13]
	v_mad_u64_u32 v[50:51], s[26:27], v144, s66, v[50:51]
	v_lshl_add_u64 v[50:51], v[88:89], 1, v[50:51]
	v_add_co_u32_e32 v50, vcc, 0xfffea000, v50
	s_nop 1
	v_addc_co_u32_e32 v51, vcc, -1, v51, vcc
	global_store_dwordx4 v[50:51], v[200:203], off offset:-8
; #define LAS __attribute__((address_space(3)))
; __device__ __forceinline__ unsigned pk2e(float lo, float hi) { typedef __bf16 b2 __attribute__((ext_vector_type(2))); b2 v; v.x = (__bf16)lo; v.y = (__bf16)hi; return __builtin_bit_cast(unsigned, v); }
; __device__ __forceinline__ float ex2(float x) { return __builtin_amdgcn_exp2f(x); }
;     __device__ __forceinline__ void operator()(const f32x4 (&acc)[2][2][4][2], const Unit& u, int wr, int wc, int fr, int fq, LAS unsigned char* hb) const {
;     ...
; #pragma unroll
;         for (int n = 0; n < 2; ++n) { asm volatile("" ::: "memory");
;             const int c4 = ch + 4 * n;
;             const f32x4 w0 = *(const f32x4*)(cw + 0 * DFF + c4), w1 = *(const f32x4*)(cw + 1 * DFF + c4), w2 = *(const f32x4*)(cw + 2 * DFF + c4), bs = *(const f32x4*)(cb + c4);
; #pragma unroll
;             for (int ai = 0; ai < 2; ++ai)
; #pragma unroll
;                 for (int m = 0; m < 4; ++m) { const int q = 8 * ai + 4 * wr + m, prev = q > 0 ? q - 1 : 0; const int lr = ai * HALF + wr * 64 + m * 16 + fr, R = R0 + lr;
;                     const int Rc = R < 0 ? 0 : R; const int b = Rc / LL, p = Rc - b * LL;
;                     const LAS unsigned char* hp = hb + (prev * H * NCH + chl + 4 * n) * 4;
;                     const f32x4 h1 = *(const LAS f32x4*)(hp + hr1 * NCH * 4), h2 = *(const LAS f32x4*)(hp + hr2 * NCH * 4);
;                     const f32x4 gv = acc[ai][0][m][n], uv = acc[ai][1][m][n];
;                     float o[4];
; #pragma unroll
;                     for (int j = 0; j < 4; ++j) { const float g = gv[j];
;                         float g1 = dpp_row_shr<1>(h1[j], g), g2 = dpp_row_shr<2>(h2[j], g);
;                         g1 = p >= 1 ? g1 : 0.f; g2 = p >= 2 ? g2 : 0.f;
;                         const float v = bs[j] + w2[j] * g + w1[j] * g1 + w0[j] * g2;
;                         const float a = v + 0.044715f * v * v * v;
;                         const float ge = v * __builtin_amdgcn_rcpf(1.f + ex2(-2.f * 0.7978845608028654f * 1.4426950408889634f * a));
;                         o[j] = ge * uv[j]; }
;                     if (lr >= H && R < TT && p >= NMETA) { u32x2 w; w.x = pk2e(o[0], o[1]); w.y = pk2e(o[2], o[3]);
;                         *(u32x2*)(ACT + ((size_t)b * SEQ + p - NMETA) * DFF + c4) = w; } }
;         }
.LBB0_908:
	s_or_b64 exec, exec, s[8:9]
	v_add_u32_e32 v48, s53, v99
	ds_read_b128 v[52:55], v48 offset:512
	v_add_u32_e32 v48, v48, v187
	ds_read_b128 v[48:51], v48
	s_waitcnt lgkmcnt(0)
	v_mov_b32_dpp v52, v44 row_shr:1 row_mask:0xf bank_mask:0xf
	v_mov_b32_dpp v53, v45 row_shr:1 row_mask:0xf bank_mask:0xf
	v_mov_b32_dpp v48, v44 row_shr:2 row_mask:0xf bank_mask:0xf
	v_mov_b32_dpp v49, v45 row_shr:2 row_mask:0xf bank_mask:0xf
	v_mov_b32_dpp v54, v46 row_shr:1 row_mask:0xf bank_mask:0xf
	v_mov_b32_dpp v50, v46 row_shr:2 row_mask:0xf bank_mask:0xf
	v_mov_b32_dpp v55, v47 row_shr:1 row_mask:0xf bank_mask:0xf
	v_mov_b32_dpp v51, v47 row_shr:2 row_mask:0xf bank_mask:0xf
	s_and_saveexec_b64 s[8:9], s[30:31]
	s_cbranch_execz .LBB0_910
	s_waitcnt vmcnt(0)
	v_pk_fma_f32 v[44:45], v[44:45], v[72:73], v[76:77]
	v_pk_fma_f32 v[46:47], v[46:47], v[74:75], v[78:79]
	v_pk_fma_f32 v[44:45], v[68:69], v[52:53], v[44:45]
	v_pk_fma_f32 v[46:47], v[70:71], v[54:55], v[46:47]
	v_pk_fma_f32 v[44:45], v[60:61], v[48:49], v[44:45]
	v_pk_fma_f32 v[46:47], v[62:63], v[50:51], v[46:47]
	v_mul_f32_e32 v48, 0x3d372713, v45
	v_mul_f32_e32 v48, v45, v48
	v_mul_f32_e32 v49, 0x3d372713, v44
	v_fma_f32 v48, v45, v48, v45
	v_mul_f32_e32 v49, v44, v49
	v_mul_f32_e32 v48, 0xc0135761, v48
	v_fma_f32 v49, v44, v49, v44
	v_exp_f32_e32 v48, v48
	v_mul_f32_e32 v49, 0xc0135761, v49
	v_mul_f32_e32 v50, 0x3d372713, v47
	v_exp_f32_e32 v52, v49
	v_mul_f32_e32 v50, v47, v50
	v_mul_f32_e32 v51, 0x3d372713, v46
	v_fma_f32 v50, v47, v50, v47
	v_mul_f32_e32 v51, v46, v51
	v_mul_f32_e32 v50, 0xc0135761, v50
	v_fma_f32 v51, v46, v51, v46
	v_add_f32_e32 v48, 1.0, v48
	v_exp_f32_e32 v50, v50
	v_mul_f32_e32 v51, 0xc0135761, v51
	v_rcp_f32_e32 v49, v48
	v_add_f32_e32 v48, 1.0, v52
	v_exp_f32_e32 v52, v51
	v_add_f32_e32 v50, 1.0, v50
	v_rcp_f32_e32 v48, v48
	v_rcp_f32_e32 v51, v50
	v_add_f32_e32 v50, 1.0, v52
	v_rcp_f32_e32 v50, v50
	v_pk_mul_f32 v[44:45], v[44:45], v[48:49]
	v_readlane_b32 s12, v237, 50
	v_pk_mul_f32 v[40:41], v[40:41], v[44:45]
	v_pk_mul_f32 v[44:45], v[46:47], v[50:51]
	v_readlane_b32 s13, v237, 51
	v_pk_mul_f32 v[42:43], v[42:43], v[44:45]
	v_cvt_pk_bf16_f32 v206, v40, v41
	v_cvt_pk_bf16_f32 v207, v42, v43
	v_mov_b64_e32 v[42:43], s[12:13]
	v_mad_u64_u32 v[42:43], s[26:27], v136, s66, v[42:43]
	v_lshl_add_u64 v[42:43], v[88:89], 1, v[42:43]
	v_add_co_u32_e32 v42, vcc, 0xfffea000, v42
	s_nop 1
	v_addc_co_u32_e32 v43, vcc, -1, v43, vcc
	global_store_dwordx4 v[42:43], v[204:207], off offset:-8
.LBB0_910:
	s_or_b64 exec, exec, s[8:9]
	v_add_u32_e32 v40, s54, v99
	ds_read_b128 v[44:47], v40 offset:512
	v_add_u32_e32 v40, v40, v187
	ds_read_b128 v[40:43], v40
	s_waitcnt lgkmcnt(0)
	v_mov_b32_dpp v44, v36 row_shr:1 row_mask:0xf bank_mask:0xf
	v_mov_b32_dpp v45, v37 row_shr:1 row_mask:0xf bank_mask:0xf
	v_mov_b32_dpp v40, v36 row_shr:2 row_mask:0xf bank_mask:0xf
	v_mov_b32_dpp v41, v37 row_shr:2 row_mask:0xf bank_mask:0xf
	v_mov_b32_dpp v46, v38 row_shr:1 row_mask:0xf bank_mask:0xf
	v_mov_b32_dpp v42, v38 row_shr:2 row_mask:0xf bank_mask:0xf
	v_mov_b32_dpp v47, v39 row_shr:1 row_mask:0xf bank_mask:0xf
	v_mov_b32_dpp v43, v39 row_shr:2 row_mask:0xf bank_mask:0xf
	s_and_saveexec_b64 s[8:9], s[34:35]
	s_cbranch_execz .LBB0_912
	s_waitcnt vmcnt(0)
	v_pk_fma_f32 v[36:37], v[36:37], v[72:73], v[76:77]
	v_pk_fma_f32 v[38:39], v[38:39], v[74:75], v[78:79]
	v_pk_fma_f32 v[36:37], v[68:69], v[44:45], v[36:37]
	v_pk_fma_f32 v[38:39], v[70:71], v[46:47], v[38:39]
	v_pk_fma_f32 v[36:37], v[60:61], v[40:41], v[36:37]
	v_pk_fma_f32 v[38:39], v[62:63], v[42:43], v[38:39]
	v_mul_f32_e32 v40, 0x3d372713, v37
	v_mul_f32_e32 v40, v37, v40
	v_mul_f32_e32 v41, 0x3d372713, v36
	v_fma_f32 v40, v37, v40, v37
	v_mul_f32_e32 v41, v36, v41
	v_mul_f32_e32 v40, 0xc0135761, v40
	v_fma_f32 v41, v36, v41, v36
	v_exp_f32_e32 v40, v40
	v_mul_f32_e32 v41, 0xc0135761, v41
	v_mul_f32_e32 v42, 0x3d372713, v39
	v_exp_f32_e32 v44, v41
	v_mul_f32_e32 v42, v39, v42
	v_mul_f32_e32 v43, 0x3d372713, v38
	v_fma_f32 v42, v39, v42, v39
	v_mul_f32_e32 v43, v38, v43
	v_mul_f32_e32 v42, 0xc0135761, v42
	v_fma_f32 v43, v38, v43, v38
	v_add_f32_e32 v40, 1.0, v40
	v_exp_f32_e32 v42, v42
	v_mul_f32_e32 v43, 0xc0135761, v43
	v_rcp_f32_e32 v41, v40
	v_add_f32_e32 v40, 1.0, v44
	v_exp_f32_e32 v44, v43
	v_add_f32_e32 v42, 1.0, v42
	v_rcp_f32_e32 v40, v40
	v_rcp_f32_e32 v43, v42
	v_add_f32_e32 v42, 1.0, v44
	v_rcp_f32_e32 v42, v42
	v_pk_mul_f32 v[36:37], v[36:37], v[40:41]
	v_readlane_b32 s12, v237, 50
	v_pk_mul_f32 v[32:33], v[32:33], v[36:37]
	v_pk_mul_f32 v[36:37], v[38:39], v[42:43]
	v_readlane_b32 s13, v237, 51
	v_pk_mul_f32 v[34:35], v[34:35], v[36:37]
	v_cvt_pk_bf16_f32 v210, v32, v33
	v_cvt_pk_bf16_f32 v211, v34, v35
	v_mov_b64_e32 v[34:35], s[12:13]
	v_mad_u64_u32 v[34:35], s[26:27], v112, s66, v[34:35]
	v_lshl_add_u64 v[34:35], v[88:89], 1, v[34:35]
	v_add_co_u32_e32 v34, vcc, 0xfffea000, v34
	s_nop 1
	v_addc_co_u32_e32 v35, vcc, -1, v35, vcc
	global_store_dwordx4 v[34:35], v[208:211], off offset:-8
; #define LAS __attribute__((address_space(3)))
; __device__ __forceinline__ unsigned pk2e(float lo, float hi) { typedef __bf16 b2 __attribute__((ext_vector_type(2))); b2 v; v.x = (__bf16)lo; v.y = (__bf16)hi; return __builtin_bit_cast(unsigned, v); }
; __device__ __forceinline__ float ex2(float x) { return __builtin_amdgcn_exp2f(x); }
;     __device__ __forceinline__ void operator()(const f32x4 (&acc)[2][2][4][2], const Unit& u, int wr, int wc, int fr, int fq, LAS unsigned char* hb) const {
;     ...
; #pragma unroll
;         for (int n = 0; n < 2; ++n) { asm volatile("" ::: "memory");
;             const int c4 = ch + 4 * n;
;             const f32x4 w0 = *(const f32x4*)(cw + 0 * DFF + c4), w1 = *(const f32x4*)(cw + 1 * DFF + c4), w2 = *(const f32x4*)(cw + 2 * DFF + c4), bs = *(const f32x4*)(cb + c4);
; #pragma unroll
;             for (int ai = 0; ai < 2; ++ai)
; #pragma unroll
;                 for (int m = 0; m < 4; ++m) { const int q = 8 * ai + 4 * wr + m, prev = q > 0 ? q - 1 : 0; const int lr = ai * HALF + wr * 64 + m * 16 + fr, R = R0 + lr;
;                     const int Rc = R < 0 ? 0 : R; const int b = Rc / LL, p = Rc - b * LL;
;                     const LAS unsigned char* hp = hb + (prev * H * NCH + chl + 4 * n) * 4;
;                     const f32x4 h1 = *(const LAS f32x4*)(hp + hr1 * NCH * 4), h2 = *(const LAS f32x4*)(hp + hr2 * NCH * 4);
;                     const f32x4 gv = acc[ai][0][m][n], uv = acc[ai][1][m][n];
;                     float o[4];
; #pragma unroll
;                     for (int j = 0; j < 4; ++j) { const float g = gv[j];
;                         float g1 = dpp_row_shr<1>(h1[j], g), g2 = dpp_row_shr<2>(h2[j], g);
;                         g1 = p >= 1 ? g1 : 0.f; g2 = p >= 2 ? g2 : 0.f;
;                         const float v = bs[j] + w2[j] * g + w1[j] * g1 + w0[j] * g2;
;                         const float a = v + 0.044715f * v * v * v;
;                         const float ge = v * __builtin_amdgcn_rcpf(1.f + ex2(-2.f * 0.7978845608028654f * 1.4426950408889634f * a));
;                         o[j] = ge * uv[j]; }
;                     if (lr >= H && R < TT && p >= NMETA) { u32x2 w; w.x = pk2e(o[0], o[1]); w.y = pk2e(o[2], o[3]);
;                         *(u32x2*)(ACT + ((size_t)b * SEQ + p - NMETA) * DFF + c4) = w; } }
;         }
.LBB0_912:
	s_or_b64 exec, exec, s[8:9]
	ds_read_b128 v[36:39], v105 offset:7696
	ds_read_b128 v[32:35], v106 offset:7184
	s_waitcnt lgkmcnt(0)
	v_mov_b32_dpp v36, v28 row_shr:1 row_mask:0xf bank_mask:0xf
	v_mov_b32_dpp v32, v28 row_shr:2 row_mask:0xf bank_mask:0xf
	v_mov_b32_dpp v37, v29 row_shr:1 row_mask:0xf bank_mask:0xf
	v_mov_b32_dpp v33, v29 row_shr:2 row_mask:0xf bank_mask:0xf
	v_mov_b32_dpp v38, v30 row_shr:1 row_mask:0xf bank_mask:0xf
	v_mov_b32_dpp v34, v30 row_shr:2 row_mask:0xf bank_mask:0xf
	v_mov_b32_dpp v39, v31 row_shr:1 row_mask:0xf bank_mask:0xf
	v_mov_b32_dpp v35, v31 row_shr:2 row_mask:0xf bank_mask:0xf
	s_and_saveexec_b64 s[8:9], s[36:37]
	s_cbranch_execz .LBB0_914
	s_waitcnt vmcnt(0)
	v_pk_fma_f32 v[28:29], v[28:29], v[72:73], v[76:77]
	v_pk_fma_f32 v[30:31], v[30:31], v[74:75], v[78:79]
	v_pk_fma_f32 v[28:29], v[68:69], v[36:37], v[28:29]
	v_pk_fma_f32 v[30:31], v[70:71], v[38:39], v[30:31]
	v_pk_fma_f32 v[28:29], v[60:61], v[32:33], v[28:29]
	v_pk_fma_f32 v[30:31], v[62:63], v[34:35], v[30:31]
	v_mul_f32_e32 v32, 0x3d372713, v29
	v_mul_f32_e32 v32, v29, v32
	v_mul_f32_e32 v33, 0x3d372713, v28
	v_fma_f32 v32, v29, v32, v29
	v_mul_f32_e32 v33, v28, v33
	v_mul_f32_e32 v32, 0xc0135761, v32
	v_fma_f32 v33, v28, v33, v28
	v_exp_f32_e32 v32, v32
	v_mul_f32_e32 v33, 0xc0135761, v33
	v_mul_f32_e32 v34, 0x3d372713, v31
	v_exp_f32_e32 v36, v33
	v_mul_f32_e32 v34, v31, v34
	v_mul_f32_e32 v35, 0x3d372713, v30
	v_fma_f32 v34, v31, v34, v31
	v_mul_f32_e32 v35, v30, v35
	v_mul_f32_e32 v34, 0xc0135761, v34
	v_fma_f32 v35, v30, v35, v30
	v_add_f32_e32 v32, 1.0, v32
	v_exp_f32_e32 v34, v34
	v_mul_f32_e32 v35, 0xc0135761, v35
	v_rcp_f32_e32 v33, v32
	v_add_f32_e32 v32, 1.0, v36
	v_exp_f32_e32 v36, v35
	v_add_f32_e32 v34, 1.0, v34
	v_rcp_f32_e32 v32, v32
	v_rcp_f32_e32 v35, v34
	v_add_f32_e32 v34, 1.0, v36
	v_rcp_f32_e32 v34, v34
	v_pk_mul_f32 v[28:29], v[28:29], v[32:33]
	v_readlane_b32 s12, v237, 50
	v_pk_mul_f32 v[24:25], v[24:25], v[28:29]
	v_pk_mul_f32 v[28:29], v[30:31], v[34:35]
	v_readlane_b32 s13, v237, 51
	v_pk_mul_f32 v[26:27], v[26:27], v[28:29]
	v_cvt_pk_bf16_f32 v214, v24, v25
	v_cvt_pk_bf16_f32 v215, v26, v27
	v_mov_b64_e32 v[26:27], s[12:13]
	v_mad_u64_u32 v[26:27], s[26:27], v104, s66, v[26:27]
	v_lshl_add_u64 v[26:27], v[88:89], 1, v[26:27]
	v_add_co_u32_e32 v26, vcc, 0xfffea000, v26
	s_nop 1
	v_addc_co_u32_e32 v27, vcc, -1, v27, vcc
	global_store_dwordx4 v[26:27], v[212:215], off offset:-8
.LBB0_914:
	s_or_b64 exec, exec, s[8:9]
	ds_read_b128 v[28:31], v97 offset:8720
	ds_read_b128 v[24:27], v98 offset:8208
	s_waitcnt lgkmcnt(0)
	v_mov_b32_dpp v28, v20 row_shr:1 row_mask:0xf bank_mask:0xf
	v_mov_b32_dpp v24, v20 row_shr:2 row_mask:0xf bank_mask:0xf
	v_mov_b32_dpp v29, v21 row_shr:1 row_mask:0xf bank_mask:0xf
	v_mov_b32_dpp v25, v21 row_shr:2 row_mask:0xf bank_mask:0xf
	v_mov_b32_dpp v30, v22 row_shr:1 row_mask:0xf bank_mask:0xf
	v_mov_b32_dpp v26, v22 row_shr:2 row_mask:0xf bank_mask:0xf
	v_mov_b32_dpp v31, v23 row_shr:1 row_mask:0xf bank_mask:0xf
	v_mov_b32_dpp v27, v23 row_shr:2 row_mask:0xf bank_mask:0xf
	s_and_saveexec_b64 s[8:9], s[38:39]
	s_cbranch_execz .LBB0_916
	s_waitcnt vmcnt(0)
	v_pk_fma_f32 v[20:21], v[20:21], v[72:73], v[76:77]
	v_pk_fma_f32 v[22:23], v[22:23], v[74:75], v[78:79]
	v_pk_fma_f32 v[20:21], v[68:69], v[28:29], v[20:21]
	v_pk_fma_f32 v[22:23], v[70:71], v[30:31], v[22:23]
	v_pk_fma_f32 v[20:21], v[60:61], v[24:25], v[20:21]
	v_pk_fma_f32 v[22:23], v[62:63], v[26:27], v[22:23]
	v_mul_f32_e32 v24, 0x3d372713, v21
	v_mul_f32_e32 v24, v21, v24
	v_mul_f32_e32 v25, 0x3d372713, v20
	v_fma_f32 v24, v21, v24, v21
	v_mul_f32_e32 v25, v20, v25
	v_mul_f32_e32 v24, 0xc0135761, v24
	v_fma_f32 v25, v20, v25, v20
	v_exp_f32_e32 v24, v24
	v_mul_f32_e32 v25, 0xc0135761, v25
	v_mul_f32_e32 v26, 0x3d372713, v23
	v_exp_f32_e32 v28, v25
	v_mul_f32_e32 v26, v23, v26
	v_mul_f32_e32 v27, 0x3d372713, v22
	v_fma_f32 v26, v23, v26, v23
	v_mul_f32_e32 v27, v22, v27
	v_mul_f32_e32 v26, 0xc0135761, v26
	v_fma_f32 v27, v22, v27, v22
	v_add_f32_e32 v24, 1.0, v24
	v_exp_f32_e32 v26, v26
	v_mul_f32_e32 v27, 0xc0135761, v27
	v_rcp_f32_e32 v25, v24
	v_add_f32_e32 v24, 1.0, v28
	v_exp_f32_e32 v28, v27
	v_add_f32_e32 v26, 1.0, v26
	v_rcp_f32_e32 v24, v24
	v_rcp_f32_e32 v27, v26
	v_add_f32_e32 v26, 1.0, v28
	v_rcp_f32_e32 v26, v26
	v_pk_mul_f32 v[20:21], v[20:21], v[24:25]
	v_readlane_b32 s12, v237, 50
	v_pk_mul_f32 v[16:17], v[16:17], v[20:21]
	v_pk_mul_f32 v[20:21], v[22:23], v[26:27]
	v_readlane_b32 s13, v237, 51
	v_pk_mul_f32 v[18:19], v[18:19], v[20:21]
	v_cvt_pk_bf16_f32 v218, v16, v17
	v_cvt_pk_bf16_f32 v219, v18, v19
	v_mov_b64_e32 v[18:19], s[12:13]
	v_mad_u64_u32 v[18:19], s[26:27], v96, s66, v[18:19]
	v_lshl_add_u64 v[18:19], v[88:89], 1, v[18:19]
	v_add_co_u32_e32 v18, vcc, 0xfffea000, v18
	s_nop 1
	v_addc_co_u32_e32 v19, vcc, -1, v19, vcc
	global_store_dwordx4 v[18:19], v[216:219], off offset:-8
; #define LAS __attribute__((address_space(3)))
; __device__ __forceinline__ unsigned pk2e(float lo, float hi) { typedef __bf16 b2 __attribute__((ext_vector_type(2))); b2 v; v.x = (__bf16)lo; v.y = (__bf16)hi; return __builtin_bit_cast(unsigned, v); }
; __device__ __forceinline__ float ex2(float x) { return __builtin_amdgcn_exp2f(x); }
;     __device__ __forceinline__ void operator()(const f32x4 (&acc)[2][2][4][2], const Unit& u, int wr, int wc, int fr, int fq, LAS unsigned char* hb) const {
;     ...
; #pragma unroll
;         for (int n = 0; n < 2; ++n) { asm volatile("" ::: "memory");
;             const int c4 = ch + 4 * n;
;             const f32x4 w0 = *(const f32x4*)(cw + 0 * DFF + c4), w1 = *(const f32x4*)(cw + 1 * DFF + c4), w2 = *(const f32x4*)(cw + 2 * DFF + c4), bs = *(const f32x4*)(cb + c4);
; #pragma unroll
;             for (int ai = 0; ai < 2; ++ai)
; #pragma unroll
;                 for (int m = 0; m < 4; ++m) { const int q = 8 * ai + 4 * wr + m, prev = q > 0 ? q - 1 : 0; const int lr = ai * HALF + wr * 64 + m * 16 + fr, R = R0 + lr;
;                     const int Rc = R < 0 ? 0 : R; const int b = Rc / LL, p = Rc - b * LL;
;                     const LAS unsigned char* hp = hb + (prev * H * NCH + chl + 4 * n) * 4;
;                     const f32x4 h1 = *(const LAS f32x4*)(hp + hr1 * NCH * 4), h2 = *(const LAS f32x4*)(hp + hr2 * NCH * 4);
;                     const f32x4 gv = acc[ai][0][m][n], uv = acc[ai][1][m][n];
;                     float o[4];
; #pragma unroll
;                     for (int j = 0; j < 4; ++j) { const float g = gv[j];
;                         float g1 = dpp_row_shr<1>(h1[j], g), g2 = dpp_row_shr<2>(h2[j], g);
;                         g1 = p >= 1 ? g1 : 0.f; g2 = p >= 2 ? g2 : 0.f;
;                         const float v = bs[j] + w2[j] * g + w1[j] * g1 + w0[j] * g2;
;                         const float a = v + 0.044715f * v * v * v;
;                         const float ge = v * __builtin_amdgcn_rcpf(1.f + ex2(-2.f * 0.7978845608028654f * 1.4426950408889634f * a));
;                         o[j] = ge * uv[j]; }
;                     if (lr >= H && R < TT && p >= NMETA) { u32x2 w; w.x = pk2e(o[0], o[1]); w.y = pk2e(o[2], o[3]);
;                         *(u32x2*)(ACT + ((size_t)b * SEQ + p - NMETA) * DFF + c4) = w; } }
;         }
.LBB0_916:
	s_or_b64 exec, exec, s[8:9]
	ds_read_b128 v[20:23], v92 offset:9744
	ds_read_b128 v[16:19], v93 offset:9232
	s_waitcnt lgkmcnt(0)
	v_mov_b32_dpp v20, v12 row_shr:1 row_mask:0xf bank_mask:0xf
	v_mov_b32_dpp v16, v12 row_shr:2 row_mask:0xf bank_mask:0xf
	v_mov_b32_dpp v21, v13 row_shr:1 row_mask:0xf bank_mask:0xf
	v_mov_b32_dpp v17, v13 row_shr:2 row_mask:0xf bank_mask:0xf
	v_mov_b32_dpp v22, v14 row_shr:1 row_mask:0xf bank_mask:0xf
	v_mov_b32_dpp v18, v14 row_shr:2 row_mask:0xf bank_mask:0xf
	v_mov_b32_dpp v23, v15 row_shr:1 row_mask:0xf bank_mask:0xf
	v_mov_b32_dpp v19, v15 row_shr:2 row_mask:0xf bank_mask:0xf
	s_and_saveexec_b64 s[8:9], s[40:41]
	s_cbranch_execz .LBB0_918
	s_waitcnt vmcnt(0)
	v_pk_fma_f32 v[12:13], v[12:13], v[72:73], v[76:77]
	v_pk_fma_f32 v[14:15], v[14:15], v[74:75], v[78:79]
	v_pk_fma_f32 v[12:13], v[68:69], v[20:21], v[12:13]
	v_pk_fma_f32 v[14:15], v[70:71], v[22:23], v[14:15]
	v_pk_fma_f32 v[12:13], v[60:61], v[16:17], v[12:13]
	v_pk_fma_f32 v[14:15], v[62:63], v[18:19], v[14:15]
	v_mul_f32_e32 v16, 0x3d372713, v13
	v_mul_f32_e32 v16, v13, v16
	v_mul_f32_e32 v17, 0x3d372713, v12
	v_fma_f32 v16, v13, v16, v13
	v_mul_f32_e32 v17, v12, v17
	v_mul_f32_e32 v16, 0xc0135761, v16
	v_fma_f32 v17, v12, v17, v12
	v_exp_f32_e32 v16, v16
	v_mul_f32_e32 v17, 0xc0135761, v17
	v_mul_f32_e32 v18, 0x3d372713, v15
	v_exp_f32_e32 v20, v17
	v_mul_f32_e32 v18, v15, v18
	v_mul_f32_e32 v19, 0x3d372713, v14
	v_fma_f32 v18, v15, v18, v15
	v_mul_f32_e32 v19, v14, v19
	v_mul_f32_e32 v18, 0xc0135761, v18
	v_fma_f32 v19, v14, v19, v14
	v_add_f32_e32 v16, 1.0, v16
	v_exp_f32_e32 v18, v18
	v_mul_f32_e32 v19, 0xc0135761, v19
	v_rcp_f32_e32 v17, v16
	v_add_f32_e32 v16, 1.0, v20
	v_exp_f32_e32 v20, v19
	v_add_f32_e32 v18, 1.0, v18
	v_rcp_f32_e32 v16, v16
	v_rcp_f32_e32 v19, v18
	v_add_f32_e32 v18, 1.0, v20
	v_rcp_f32_e32 v18, v18
	v_pk_mul_f32 v[12:13], v[12:13], v[16:17]
	v_readlane_b32 s12, v237, 50
	v_pk_mul_f32 v[8:9], v[8:9], v[12:13]
	v_pk_mul_f32 v[12:13], v[14:15], v[18:19]
	v_readlane_b32 s13, v237, 51
	v_pk_mul_f32 v[10:11], v[10:11], v[12:13]
	v_cvt_pk_bf16_f32 v230, v8, v9
	v_cvt_pk_bf16_f32 v231, v10, v11
	v_mov_b64_e32 v[10:11], s[12:13]
	v_mad_u64_u32 v[10:11], s[26:27], v90, s66, v[10:11]
	v_lshl_add_u64 v[10:11], v[88:89], 1, v[10:11]
	v_add_co_u32_e32 v10, vcc, 0xfffea000, v10
	s_nop 1
	v_addc_co_u32_e32 v11, vcc, -1, v11, vcc
	global_store_dwordx4 v[10:11], v[228:231], off offset:-8
.LBB0_918:
	s_or_b64 exec, exec, s[8:9]
	ds_read_b128 v[12:15], v94 offset:10768
	ds_read_b128 v[8:11], v95 offset:10256
	s_waitcnt lgkmcnt(0)
	v_mov_b32_dpp v12, v4 row_shr:1 row_mask:0xf bank_mask:0xf
	v_mov_b32_dpp v8, v4 row_shr:2 row_mask:0xf bank_mask:0xf
	v_mov_b32_dpp v13, v5 row_shr:1 row_mask:0xf bank_mask:0xf
	v_mov_b32_dpp v9, v5 row_shr:2 row_mask:0xf bank_mask:0xf
	v_mov_b32_dpp v14, v6 row_shr:1 row_mask:0xf bank_mask:0xf
	v_mov_b32_dpp v10, v6 row_shr:2 row_mask:0xf bank_mask:0xf
	v_mov_b32_dpp v15, v7 row_shr:1 row_mask:0xf bank_mask:0xf
	v_mov_b32_dpp v11, v7 row_shr:2 row_mask:0xf bank_mask:0xf
	s_and_saveexec_b64 s[8:9], s[6:7]
	s_cbranch_execz .LBB0_920
	s_waitcnt vmcnt(0)
	v_pk_fma_f32 v[4:5], v[4:5], v[72:73], v[76:77]
	v_pk_fma_f32 v[6:7], v[6:7], v[74:75], v[78:79]
	v_pk_fma_f32 v[4:5], v[68:69], v[12:13], v[4:5]
	v_pk_fma_f32 v[6:7], v[70:71], v[14:15], v[6:7]
	v_pk_fma_f32 v[4:5], v[60:61], v[8:9], v[4:5]
	v_pk_fma_f32 v[6:7], v[62:63], v[10:11], v[6:7]
	v_mul_f32_e32 v8, 0x3d372713, v5
	v_mul_f32_e32 v8, v5, v8
	v_mul_f32_e32 v9, 0x3d372713, v4
	v_fma_f32 v8, v5, v8, v5
	v_mul_f32_e32 v9, v4, v9
	v_mul_f32_e32 v8, 0xc0135761, v8
	v_fma_f32 v9, v4, v9, v4
	v_exp_f32_e32 v8, v8
	v_mul_f32_e32 v9, 0xc0135761, v9
	v_mul_f32_e32 v10, 0x3d372713, v7
	v_exp_f32_e32 v12, v9
	v_mul_f32_e32 v10, v7, v10
	v_mul_f32_e32 v11, 0x3d372713, v6
	v_fma_f32 v10, v7, v10, v7
	v_mul_f32_e32 v11, v6, v11
	v_mul_f32_e32 v10, 0xc0135761, v10
	v_fma_f32 v11, v6, v11, v6
	v_add_f32_e32 v8, 1.0, v8
	v_exp_f32_e32 v10, v10
	v_mul_f32_e32 v11, 0xc0135761, v11
	v_rcp_f32_e32 v9, v8
	v_add_f32_e32 v8, 1.0, v12
	v_exp_f32_e32 v12, v11
	v_add_f32_e32 v10, 1.0, v10
	v_rcp_f32_e32 v8, v8
	v_rcp_f32_e32 v11, v10
	v_add_f32_e32 v10, 1.0, v12
	v_rcp_f32_e32 v10, v10
	v_pk_mul_f32 v[4:5], v[4:5], v[8:9]
	v_readlane_b32 s6, v237, 50
	v_pk_mul_f32 v[0:1], v[0:1], v[4:5]
	v_pk_mul_f32 v[4:5], v[6:7], v[10:11]
	v_readlane_b32 s7, v237, 51
	v_pk_mul_f32 v[2:3], v[2:3], v[4:5]
	v_cvt_pk_bf16_f32 v234, v0, v1
	v_cvt_pk_bf16_f32 v235, v2, v3
	v_mov_b64_e32 v[2:3], s[6:7]
	v_mad_u64_u32 v[2:3], s[6:7], v91, s66, v[2:3]
	v_lshl_add_u64 v[2:3], v[88:89], 1, v[2:3]
	v_add_co_u32_e32 v2, vcc, 0xfffea000, v2
	s_nop 1
	v_addc_co_u32_e32 v3, vcc, -1, v3, vcc
	global_store_dwordx4 v[2:3], v[232:235], off offset:-8
